# adds: exact DPP row shuffles instead of ds_bpermute in sb/dil norms, SB prologue counted wait, grid barrier waiters poll TOP directly (one hop less)
# speedup vs baseline: 1.0153x; 1.0062x over previous
; __device__ __forceinline__ int tidx() { int t = threadIdx.x; asm volatile("" : "+v"(t)); return t; }
; __device__ __forceinline__ void stage_rows128_norm(bf16_t* dst, const bf16_t* P, int r0, int rstride, int col, const float* __restrict__ gain, float qs) {
;     const int tid = tidx(), lane = tid & 63;
;     const f32x4 g0 = *(const f32x4*)(gain + (tid & 15) * 8), g1 = *(const f32x4*)(gain + (tid & 15) * 8 + 4);
; #pragma unroll
;     for (int i = 0; i < 4; ++i) {
;         const int idx = tid + 512 * i, r = idx >> 4, ch = idx & 15;
;         const u32x4 raw = *(const u32x4*)(P + pidx(r0 + r * rstride, col + ch * 8));
;         float v[8] = {bflo(raw[0]), bfhi(raw[0]), bflo(raw[1]), bfhi(raw[1]), bflo(raw[2]), bfhi(raw[2]), bflo(raw[3]), bfhi(raw[3])};
;         float ss = 0.f;
; #pragma unroll
;         for (int j = 0; j < 8; ++j) ss += v[j] * v[j];
;         ss += shx(ss, 1, lane); ss += shx(ss, 2, lane); ss += shx(ss, 4, lane); ss += shx(ss, 8, lane);
;         const float inv = rsqrtf(ss * (1.f / 128.f) + EPS) * qs;
; __device__ __forceinline__ void dil_item(const Params& p, int item, int l, unsigned char* lds) {
;     const int tid = tidx(), w = tid >> 6, lane = tid & 63, fr = lane & 15, fq = lane >> 4;
;     const bf16_t* P = (const bf16_t*)(p.ws + W_PROJ);
;     float* ODG = (float*)(p.ws + W_ODG); float* LSE = (float*)(p.ws + W_LSE);
;     const int g = item >> 7, rem = item & 127, hh = rem >> 6, s6 = rem & 63;
;     const int r = g == 0 ? 1 : (g == 1 ? 4 : 16), nb = 64 / r, rho = s6 / nb, n = s6 % nb;
;     const int head = 2 * g + hh;
;     const float slope = exp2f(-8.f * (float)(head + 1) / 6.f) * (float)r;
;     bf16_t* Qs = (bf16_t*)(lds + AT_Q);
;     const float* gq = p.in[9] + l * 128; const float* gk = p.in[10] + l * 128;
;     const f32x4 gk0 = *(const f32x4*)(gk + (tid & 15) * 8), gk1 = *(const f32x4*)(gk + (tid & 15) * 8 + 4);
;     const int kcol = C_KDIL + head * 128, vcol = C_VDIL + head * 128;
;     __syncthreads();
;     TileRegs tr;
;     int c = n == 0 ? 2 : 0;
;     tile_load(tr, P, (128 * (n - 1) + 64 * c) * r + rho, r, kcol, vcol, tid);
;     stage_rows128_norm(Qs, P, (128 * n) * r + rho, r, C_QDIL + head * 128, gq, 0.08838834764831845f);
;     tile_write(tr, lds + AT_BUF, gk0, gk1, tid, lane);
;     tile_load(tr, P, (128 * (n - 1) + 64 * (c + 1)) * r + rho, r, kcol, vcol, tid);
.LBB0_107:
	s_and_b64 vcc, exec, s[0:1]
	s_cbranch_vccz .LBB0_119
	s_add_i32 s0, s15, 0xfffffe80
	s_lshr_b32 s16, s0, 7
	s_bfe_u32 s5, s15, 0x10006
	s_and_b32 s1, s15, 63
	s_cmp_eq_u32 s16, 1
	s_cselect_b32 s4, 4, 16
	s_cselect_b32 s17, 2, 4
	s_cmpk_lt_u32 s0, 0x80
	s_cselect_b32 s17, 0, s17
	s_cselect_b32 s31, 1, s4
	s_lshr_b32 s0, 64, s17
	s_xor_b32 s4, s17, 6
	s_add_i32 s0, s0, -1
	s_lshr_b32 s18, s1, s4
	s_and_b32 s1, s0, s1
	s_lshl_b32 s0, s16, 1
	s_or_b32 s4, s0, s5
	s_not_b32 s0, s4
	s_lshl_b32 s19, s4, 7
	s_lshl_b32 s0, s0, 3
	s_add_i32 s30, s19, 0xf00
	s_cmp_eq_u32 s1, 0
	s_cselect_b32 s25, 2, 0
	v_mov_b32_e32 v39, v185
	s_lshl_b32 s19, s1, 7
	s_lshl_b32 s28, s25, 6
	s_add_i32 s1, s28, s19
	v_lshlrev_b32_e32 v0, 3, v39
	v_and_b32_e32 v85, 0x78, v0
	v_readlane_b32 s36, v245, 49
	s_add_i32 s33, s1, 0xffffff80
	v_lshlrev_b32_e32 v0, 2, v85
	v_readlane_b32 s37, v245, 50
	s_lshl_b32 s33, s33, s17
	s_waitcnt vmcnt(0)
	v_add_u32_e32 v20, 0x200, v39
	s_nop 1
	global_load_dwordx4 v[2:5], v0, s[36:37] offset:16
	global_load_dwordx4 v[6:9], v0, s[36:37]
	s_or_b32 s33, s33, s18
	s_lshl_b32 s36, s4, 21
	v_ashrrev_i32_e32 v52, 4, v20
	s_add_u32 s36, s2, s36
	v_lshlrev_b32_e32 v88, s17, v52
	s_addc_u32 s37, s3, 0
	v_lshlrev_b32_e32 v0, 1, v85
	v_add_u32_e32 v16, s33, v88
	v_and_b32_e32 v84, 63, v39
	v_lshl_add_u64 v[10:11], s[36:37], 0, v[0:1]
	s_mov_b64 s[38:39], 0x3000000
	v_ashrrev_i32_e32 v17, 31, v16
	s_waitcnt lgkmcnt(0)
	v_lshl_add_u64 v[74:75], v[10:11], 0, s[38:39]
	v_lshlrev_b32_e32 v86, s17, v84
	v_ashrrev_i32_e32 v67, 3, v39
	v_lshlrev_b64 v[16:17], 8, v[16:17]
	v_ashrrev_i32_e32 v68, 3, v20
	v_add_u32_e32 v10, s33, v86
	v_ashrrev_i32_e32 v66, 4, v39
	v_add_u32_e32 v14, s30, v67
	v_lshl_add_u64 v[18:19], v[74:75], 0, v[16:17]
	v_add_u32_e32 v16, s30, v68
	v_ashrrev_i32_e32 v11, 31, v10
	v_lshlrev_b32_e32 v87, s17, v66
	v_ashrrev_i32_e32 v14, 7, v14
	v_ashrrev_i32_e32 v16, 7, v16
	v_lshlrev_b64 v[10:11], 8, v[10:11]
	v_add_u32_e32 v12, s33, v87
	v_ashrrev_i32_e32 v15, 31, v14
	v_ashrrev_i32_e32 v17, 31, v16
	v_lshl_add_u64 v[10:11], s[2:3], 0, v[10:11]
	v_ashrrev_i32_e32 v13, 31, v12
	v_and_b32_e32 v38, 0x78, v67
	v_lshlrev_b64 v[76:77], 21, v[14:15]
	v_and_b32_e32 v40, 0x78, v68
	v_lshlrev_b64 v[78:79], 21, v[16:17]
	v_lshlrev_b64 v[12:13], 8, v[12:13]
	v_lshl_add_u64 v[14:15], v[10:11], 0, v[76:77]
	v_lshlrev_b32_e32 v42, 1, v38
	v_mov_b32_e32 v43, v1
	v_lshl_add_u64 v[10:11], v[10:11], 0, v[78:79]
	v_lshlrev_b32_e32 v44, 1, v40
	v_mov_b32_e32 v45, v1
	v_lshl_add_u64 v[12:13], v[74:75], 0, v[12:13]
	v_lshl_add_u64 v[14:15], v[14:15], 0, v[42:43]
	v_lshl_add_u64 v[10:11], v[10:11], 0, v[44:45]
	v_mov_b32_e32 v53, v185
	s_waitcnt lgkmcnt(0)
	s_barrier
	flat_load_dwordx4 v[30:33], v[12:13]
	s_nop 0
	flat_load_dwordx4 v[14:17], v[14:15]
	s_nop 0
	flat_load_dwordx4 v[26:29], v[18:19]
	s_nop 0
	flat_load_dwordx4 v[10:13], v[10:11]
	v_mov_b32_e32 v47, v1
	v_lshlrev_b32_e32 v18, 3, v53
	v_and_b32_e32 v20, 0x78, v18
	v_lshlrev_b32_e32 v46, 1, v20
	s_lshl_b32 s30, s19, s17
	v_lshl_add_u64 v[18:19], s[36:37], 0, v[46:47]
	s_mov_b64 s[36:37], 0x2400000
	v_ashrrev_i32_e32 v64, 4, v53
	s_or_b32 s30, s30, s18
	v_lshl_add_u64 v[48:49], v[18:19], 0, s[36:37]
	v_lshlrev_b32_e32 v18, s17, v64
	v_add_u32_e32 v18, s30, v18
	v_ashrrev_i32_e32 v19, 31, v18
	v_lshlrev_b64 v[18:19], 8, v[18:19]
	v_lshl_add_u64 v[18:19], v[48:49], 0, v[18:19]
	flat_load_dwordx4 v[34:37], v[18:19]
	s_lshl_b32 s36, 0x2000, s17
	s_mov_b32 s37, 0
	v_lshl_add_u64 v[152:153], v[18:19], 0, s[36:37]
	flat_load_dwordx4 v[156:159], v[152:153]
	v_lshl_add_u64 v[152:153], v[152:153], 0, s[36:37]
	flat_load_dwordx4 v[160:163], v[152:153]
	v_lshl_add_u64 v[152:153], v[152:153], 0, s[36:37]
	flat_load_dwordx4 v[164:167], v[152:153]
	v_readlane_b32 s36, v245, 47
	v_lshlrev_b32_e32 v18, 2, v20
	v_readlane_b32 s37, v245, 48
	s_nop 4
	global_load_dwordx4 v[22:25], v18, s[36:37]
	s_nop 0
	global_load_dwordx4 v[18:21], v18, s[36:37] offset:16
	v_lshlrev_b32_e32 v47, 2, v53
	v_bitop3_b32 v41, v47, 4, v211 bitop3:0x6c
	v_add_u32_e32 v46, 0, v46
	s_movk_i32 s38, 0x110
	s_movk_i32 s33, 0x88
	v_mul_lo_u32 v90, v66, s33
	v_mul_lo_u32 v96, v52, s33
	v_add_u32_e32 v0, 0, v0
	v_lshl_add_u32 v100, v90, 1, v0
	v_lshl_add_u32 v102, v96, 1, v0
	v_add_u32_e32 v0, 0x600, v53
	v_ashrrev_i32_e32 v98, 4, v0
	v_cvt_f32_i32_e32 v101, s0
	s_sub_i32 s0, s1, 64
	s_lshl_b32 s0, s0, s17
	s_or_b32 s33, s0, s18
	v_lshlrev_b32_e32 v89, 2, v84
	v_xor_b32_e32 v91, 4, v89
	v_xor_b32_e32 v92, 8, v89
	v_xor_b32_e32 v93, 16, v89
	v_xor_b32_e32 v94, 32, v89
	s_mov_b32 s39, 0x40c00000
	v_and_b32_e32 v80, 15, v39
	v_mov_b32_e32 v108, 0
	v_mul_u32_u24_e32 v106, 0x110, v80
	s_waitcnt vmcnt(0) lgkmcnt(0)
	v_lshlrev_b32_e32 v66, 16, v28
	v_lshlrev_b32_e32 v62, 16, v34
	v_and_b32_e32 v63, 0xffff0000, v34
	v_lshlrev_b32_e32 v58, 16, v35
	v_and_b32_e32 v59, 0xffff0000, v35
	v_pk_mul_f32 v[34:35], v[62:63], v[62:63]
	v_pk_mul_f32 v[60:61], v[58:59], v[58:59]
	v_add_f32_e32 v34, v34, v35
	v_lshlrev_b32_e32 v56, 16, v36
	v_and_b32_e32 v57, 0xffff0000, v36
	v_add_f32_e32 v34, v60, v34
	v_lshlrev_b32_e32 v54, 16, v37
	v_and_b32_e32 v55, 0xffff0000, v37
	v_pk_mul_f32 v[36:37], v[56:57], v[56:57]
	v_add_f32_e32 v34, v61, v34
	v_add_f32_e32 v34, v36, v34
	v_pk_mul_f32 v[50:51], v[54:55], v[54:55]
	v_add_f32_e32 v34, v37, v34
	v_add_f32_e32 v34, v50, v34
	v_add_f32_e32 v34, v51, v34
	s_nop 1
	v_mov_b32_dpp v35, v34 quad_perm:[1,0,3,2] row_mask:0xf bank_mask:0xf
	v_bitop3_b32 v51, v47, 8, v211 bitop3:0x6c
	v_bitop3_b32 v50, v47, 16, v211 bitop3:0x6c
	v_bitop3_b32 v47, v47, 32, v211 bitop3:0x6c
	s_waitcnt lgkmcnt(0)
; __device__ __forceinline__ unsigned pk2(float lo, float hi) { const f32v2_t v = {lo, hi}; return __builtin_bit_cast(unsigned, __builtin_convertvector(v, bf16v2_t)); }
; __device__ __forceinline__ int tidx() { int t = threadIdx.x; asm volatile("" : "+v"(t)); return t; }
; __device__ __forceinline__ float shx(float v, int mask, int lane) { return __int_as_float(__builtin_amdgcn_ds_bpermute((lane ^ mask) << 2, __float_as_int(v))); }
; __device__ __forceinline__ size_t pidx(int row, int col) { return (size_t)(col >> 7) * ((size_t)T * 128) + (size_t)row * 128 + (col & 127); }
; __device__ __forceinline__ float bflo(unsigned u) { return __uint_as_float(u << 16); }
; __device__ __forceinline__ float bfhi(unsigned u) { return __uint_as_float(u & 0xffff0000u); }
; __device__ __forceinline__ void stage_rows128_norm(bf16_t* dst, const bf16_t* P, int r0, int rstride, int col, const float* __restrict__ gain, float qs) {
;     const int tid = tidx(), lane = tid & 63;
;     const f32x4 g0 = *(const f32x4*)(gain + (tid & 15) * 8), g1 = *(const f32x4*)(gain + (tid & 15) * 8 + 4);
; #pragma unroll
;     for (int i = 0; i < 4; ++i) {
;         const int idx = tid + 512 * i, r = idx >> 4, ch = idx & 15;
;         const u32x4 raw = *(const u32x4*)(P + pidx(r0 + r * rstride, col + ch * 8));
;         float v[8] = {bflo(raw[0]), bfhi(raw[0]), bflo(raw[1]), bfhi(raw[1]), bflo(raw[2]), bfhi(raw[2]), bflo(raw[3]), bfhi(raw[3])};
;         float ss = 0.f;
; #pragma unroll
;         for (int j = 0; j < 8; ++j) ss += v[j] * v[j];
;         ss += shx(ss, 1, lane); ss += shx(ss, 2, lane); ss += shx(ss, 4, lane); ss += shx(ss, 8, lane);
;         const float inv = rsqrtf(ss * (1.f / 128.f) + EPS) * qs;
;         u32x4 o = {pk2(v[0] * inv * g0[0], v[1] * inv * g0[1]), pk2(v[2] * inv * g0[2], v[3] * inv * g0[3]),
;                    pk2(v[4] * inv * g1[0], v[5] * inv * g1[1]), pk2(v[6] * inv * g1[2], v[7] * inv * g1[3])};
;         *(u32x4*)(dst + r * 136 + ch * 8) = o;
;     }
; }
	v_add_f32_e32 v34, v34, v35
	s_nop 1
	v_mov_b32_dpp v35, v34 quad_perm:[2,3,0,1] row_mask:0xf bank_mask:0xf
	s_waitcnt lgkmcnt(0)
	v_add_f32_e32 v34, v34, v35
	s_nop 1
	v_mov_b32_dpp v35, v34 row_shl:4 row_mask:0xf bank_mask:0x5
	v_mov_b32_dpp v35, v34 row_shr:4 row_mask:0xf bank_mask:0xa
	s_waitcnt lgkmcnt(0)
	v_add_f32_e32 v34, v34, v35
	s_nop 1
	v_mov_b32_dpp v35, v34 row_shl:8 row_mask:0xf bank_mask:0x3
	v_mov_b32_dpp v35, v34 row_shr:8 row_mask:0xf bank_mask:0xc
	s_waitcnt lgkmcnt(0)
	v_add_f32_e32 v34, v34, v35
	v_fmamk_f32 v34, v34, 0x3c000000, v184
	v_mul_f32_e32 v35, 0x4b800000, v34
	v_cmp_gt_f32_e32 vcc, s90, v34
	s_nop 1
	v_cndmask_b32_e32 v34, v34, v35, vcc
	v_rsq_f32_e32 v34, v34
	s_nop 0
	v_mul_f32_e32 v35, 0x45800000, v34
	v_cndmask_b32_e32 v34, v34, v35, vcc
	v_mul_f32_e32 v60, 0x3db504f3, v34
	v_pk_mul_f32 v[34:35], v[60:61], v[62:63] op_sel_hi:[0,1]
	v_pk_mul_f32 v[36:37], v[60:61], v[58:59] op_sel_hi:[0,1]
	v_pk_mul_f32 v[34:35], v[22:23], v[34:35]
	v_pk_mul_f32 v[36:37], v[24:25], v[36:37]
	v_cvt_pk_bf16_f32 v34, v34, v35
	v_cvt_pk_bf16_f32 v35, v36, v37
	v_pk_mul_f32 v[36:37], v[60:61], v[56:57] op_sel_hi:[0,1]
	v_pk_mul_f32 v[54:55], v[60:61], v[54:55] op_sel_hi:[0,1]
	v_pk_mul_f32 v[36:37], v[18:19], v[36:37]
	v_pk_mul_f32 v[54:55], v[20:21], v[54:55]
	v_cvt_pk_bf16_f32 v36, v36, v37
	v_cvt_pk_bf16_f32 v37, v54, v55
	v_mad_u64_u32 v[54:55], s[36:37], v64, s38, v[46:47]
	ds_write_b128 v54, v[34:37]
	v_add_u32_e32 v34, 0x200, v53
	v_ashrrev_i32_e32 v69, 4, v34
	v_lshlrev_b32_e32 v34, s17, v69
	v_add_u32_e32 v34, s30, v34
	v_ashrrev_i32_e32 v35, 31, v34
	v_lshlrev_b64 v[34:35], 8, v[34:35]
	v_lshl_add_u64 v[34:35], v[48:49], 0, v[34:35]
	v_mov_b64_e32 v[34:35], v[156:157]
	v_mov_b64_e32 v[36:37], v[158:159]
	s_waitcnt lgkmcnt(0)
	v_lshlrev_b32_e32 v58, 16, v34
	v_and_b32_e32 v59, 0xffff0000, v34
	v_lshlrev_b32_e32 v54, 16, v37
	v_and_b32_e32 v55, 0xffff0000, v37
	v_lshlrev_b32_e32 v56, 16, v36
	v_and_b32_e32 v57, 0xffff0000, v36
	v_lshlrev_b32_e32 v36, 16, v35
	v_and_b32_e32 v37, 0xffff0000, v35
	v_pk_mul_f32 v[64:65], v[58:59], v[58:59]
	v_pk_mul_f32 v[62:63], v[36:37], v[36:37]
	v_add_f32_e32 v64, v64, v65
	v_add_f32_e32 v62, v62, v64
	v_pk_mul_f32 v[60:61], v[56:57], v[56:57]
	v_add_f32_e32 v62, v63, v62
	v_add_f32_e32 v60, v60, v62
	v_pk_mul_f32 v[34:35], v[54:55], v[54:55]
	v_add_f32_e32 v60, v61, v60
	v_add_f32_e32 v34, v34, v60
	v_add_f32_e32 v34, v35, v34
	s_nop 1
	v_mov_b32_dpp v35, v34 quad_perm:[1,0,3,2] row_mask:0xf bank_mask:0xf
	v_add_u32_e32 v60, 0x400, v53
	v_ashrrev_i32_e32 v64, 4, v60
	v_mad_u64_u32 v[60:61], s[36:37], v69, s38, v[46:47]
	s_waitcnt lgkmcnt(0)
	v_add_f32_e32 v34, v34, v35
	s_nop 1
	v_mov_b32_dpp v35, v34 quad_perm:[2,3,0,1] row_mask:0xf bank_mask:0xf
	s_movk_i32 s36, 0x48
	v_and_b32_e32 v65, 0xffff0000, v29
	s_waitcnt lgkmcnt(0)
	v_add_f32_e32 v34, v34, v35
	s_nop 1
	v_mov_b32_dpp v35, v34 row_shl:4 row_mask:0xf bank_mask:0x5
	v_mov_b32_dpp v35, v34 row_shr:4 row_mask:0xf bank_mask:0xa
	s_waitcnt lgkmcnt(0)
	v_add_f32_e32 v35, v34, v35
	s_nop 1
	v_mov_b32_dpp v62, v35 row_shl:8 row_mask:0xf bank_mask:0x3
	v_mov_b32_dpp v62, v35 row_shr:8 row_mask:0xf bank_mask:0xc
	v_lshlrev_b32_e32 v34, s17, v64
	v_add_u32_e32 v34, s30, v34
	s_waitcnt lgkmcnt(0)
	v_add_f32_e32 v35, v35, v62
	v_fmamk_f32 v35, v35, 0x3c000000, v184
	v_mul_f32_e32 v61, 0x4b800000, v35
	v_cmp_gt_f32_e32 vcc, s90, v35
	s_nop 1
	v_cndmask_b32_e32 v35, v35, v61, vcc
	v_rsq_f32_e32 v61, v35
	v_ashrrev_i32_e32 v35, 31, v34
	v_lshlrev_b64 v[34:35], 8, v[34:35]
	v_lshl_add_u64 v[62:63], v[48:49], 0, v[34:35]
	v_mul_f32_e32 v34, 0x45800000, v61
	v_cndmask_b32_e32 v34, v61, v34, vcc
	v_mul_f32_e32 v34, 0x3db504f3, v34
	v_pk_mul_f32 v[58:59], v[34:35], v[58:59] op_sel_hi:[0,1]
	v_pk_mul_f32 v[36:37], v[34:35], v[36:37] op_sel_hi:[0,1]
	v_pk_mul_f32 v[56:57], v[34:35], v[56:57] op_sel_hi:[0,1]
	v_pk_mul_f32 v[34:35], v[34:35], v[54:55] op_sel_hi:[0,1]
	v_pk_mul_f32 v[54:55], v[22:23], v[58:59]
	v_pk_mul_f32 v[36:37], v[24:25], v[36:37]
	v_pk_mul_f32 v[56:57], v[18:19], v[56:57]
	v_pk_mul_f32 v[58:59], v[20:21], v[34:35]
	v_cvt_pk_bf16_f32 v34, v54, v55
	v_cvt_pk_bf16_f32 v35, v36, v37
	v_cvt_pk_bf16_f32 v36, v56, v57
	v_cvt_pk_bf16_f32 v37, v58, v59
	ds_write_b128 v60, v[34:37]
	v_mov_b64_e32 v[34:35], v[160:161]
	v_mov_b64_e32 v[36:37], v[162:163]
	v_and_b32_e32 v54, 0x1ffffff8, v67
	v_and_b32_e32 v56, 0x1ffffff8, v68
	v_lshl_add_u32 v55, v84, 1, 0
	v_mul_lo_u32 v95, v54, s36
	v_mul_lo_u32 v97, v56, s36
	v_lshl_add_u32 v81, v95, 1, v55
	v_lshl_add_u32 v103, v97, 1, v55
	v_and_b32_e32 v67, 0xffff0000, v28
	v_div_scale_f32 v104, s[36:37], s39, s39, v101
	v_rcp_f32_e32 v105, v104
	s_waitcnt lgkmcnt(0)
	v_lshlrev_b32_e32 v56, 16, v34
	v_and_b32_e32 v57, 0xffff0000, v34
	v_lshlrev_b32_e32 v52, 16, v37
	v_and_b32_e32 v53, 0xffff0000, v37
	v_lshlrev_b32_e32 v54, 16, v36
	v_and_b32_e32 v55, 0xffff0000, v36
	v_lshlrev_b32_e32 v36, 16, v35
	v_and_b32_e32 v37, 0xffff0000, v35
	v_pk_mul_f32 v[62:63], v[56:57], v[56:57]
	v_pk_mul_f32 v[60:61], v[36:37], v[36:37]
	v_add_f32_e32 v0, v62, v63
	v_add_f32_e32 v0, v60, v0
	v_pk_mul_f32 v[58:59], v[54:55], v[54:55]
	v_add_f32_e32 v0, v61, v0
	v_add_f32_e32 v0, v58, v0
	v_pk_mul_f32 v[34:35], v[52:53], v[52:53]
	v_add_f32_e32 v0, v59, v0
	v_add_f32_e32 v0, v34, v0
	v_add_f32_e32 v0, v35, v0
	s_nop 1
	v_mov_b32_dpp v35, v0 quad_perm:[1,0,3,2] row_mask:0xf bank_mask:0xf
	v_mad_u64_u32 v[58:59], s[0:1], v64, s38, v[46:47]
	v_lshlrev_b32_e32 v62, 16, v30
	v_and_b32_e32 v63, 0xffff0000, v30
	s_waitcnt lgkmcnt(0)
; __device__ __forceinline__ unsigned pk2(float lo, float hi) { const f32v2_t v = {lo, hi}; return __builtin_bit_cast(unsigned, __builtin_convertvector(v, bf16v2_t)); }
; __device__ __forceinline__ float shx(float v, int mask, int lane) { return __int_as_float(__builtin_amdgcn_ds_bpermute((lane ^ mask) << 2, __float_as_int(v))); }
; __device__ __forceinline__ void stage_rows128_norm(bf16_t* dst, const bf16_t* P, int r0, int rstride, int col, const float* __restrict__ gain, float qs) {
;     ...
;         const int idx = tid + 512 * i, r = idx >> 4, ch = idx & 15;
;         const u32x4 raw = *(const u32x4*)(P + pidx(r0 + r * rstride, col + ch * 8));
;         float v[8] = {bflo(raw[0]), bfhi(raw[0]), bflo(raw[1]), bfhi(raw[1]), bflo(raw[2]), bfhi(raw[2]), bflo(raw[3]), bfhi(raw[3])};
;         float ss = 0.f;
; #pragma unroll
;         for (int j = 0; j < 8; ++j) ss += v[j] * v[j];
;         ss += shx(ss, 1, lane); ss += shx(ss, 2, lane); ss += shx(ss, 4, lane); ss += shx(ss, 8, lane);
;         const float inv = rsqrtf(ss * (1.f / 128.f) + EPS) * qs;
;         u32x4 o = {pk2(v[0] * inv * g0[0], v[1] * inv * g0[1]), pk2(v[2] * inv * g0[2], v[3] * inv * g0[3]),
;                    pk2(v[4] * inv * g1[0], v[5] * inv * g1[1]), pk2(v[6] * inv * g1[2], v[7] * inv * g1[3])};
;         *(u32x4*)(dst + r * 136 + ch * 8) = o;
;     }
; }
; __device__ __forceinline__ void tile_write(const TileRegs& t, unsigned char* buf, const f32x4& g0, const f32x4& g1, int tid, int lane) {
;     bf16_t* Ks = (bf16_t*)buf; bf16_t* VT = (bf16_t*)(buf + AT_VOFF);
; #pragma unroll
;     for (int i = 0; i < 2; ++i) {
;         const int idx = tid + 512 * i, r = idx >> 4, ch = idx & 15;
;         const u32x4 raw = t.k[i];
;         float v[8] = {bflo(raw[0]), bfhi(raw[0]), bflo(raw[1]), bfhi(raw[1]), bflo(raw[2]), bfhi(raw[2]), bflo(raw[3]), bfhi(raw[3])};
;         float ss = 0.f;
; #pragma unroll
;         for (int j = 0; j < 8; ++j) ss += v[j] * v[j];
;         ss += shx(ss, 1, lane); ss += shx(ss, 2, lane); ss += shx(ss, 4, lane); ss += shx(ss, 8, lane);
;         const float inv = rsqrtf(ss * (1.f / 128.f) + EPS);
;         u32x4 o = {pk2(v[0] * inv * g0[0], v[1] * inv * g0[1]), pk2(v[2] * inv * g0[2], v[3] * inv * g0[3]),
;                    pk2(v[4] * inv * g1[0], v[5] * inv * g1[1]), pk2(v[6] * inv * g1[2], v[7] * inv * g1[3])};
;         *(u32x4*)(Ks + r * 136 + ch * 8) = o;
	v_add_f32_e32 v0, v0, v35
	s_nop 1
	v_mov_b32_dpp v59, v0 quad_perm:[2,3,0,1] row_mask:0xf bank_mask:0xf
	v_lshlrev_b32_e32 v34, s17, v98
	v_add_u32_e32 v34, s30, v34
	v_ashrrev_i32_e32 v35, 31, v34
	v_lshlrev_b64 v[34:35], 8, v[34:35]
	s_waitcnt lgkmcnt(0)
	v_add_f32_e32 v0, v0, v59
	s_nop 1
	v_mov_b32_dpp v59, v0 row_shl:4 row_mask:0xf bank_mask:0x5
	v_mov_b32_dpp v59, v0 row_shr:4 row_mask:0xf bank_mask:0xa
	v_lshl_add_u64 v[34:35], v[48:49], 0, v[34:35]
	v_lshlrev_b32_e32 v48, 16, v33
	v_and_b32_e32 v49, 0xffff0000, v33
	v_lshlrev_b32_e32 v60, 16, v32
	s_waitcnt lgkmcnt(0)
	v_add_f32_e32 v0, v0, v59
	s_nop 1
	v_mov_b32_dpp v59, v0 row_shl:8 row_mask:0xf bank_mask:0x3
	v_mov_b32_dpp v59, v0 row_shr:8 row_mask:0xf bank_mask:0xc
	v_and_b32_e32 v61, 0xffff0000, v32
	v_lshlrev_b32_e32 v32, 16, v31
	v_and_b32_e32 v33, 0xffff0000, v31
	v_lshlrev_b32_e32 v64, 16, v29
	s_waitcnt lgkmcnt(0)
	v_add_f32_e32 v0, v0, v59
	v_fmamk_f32 v0, v0, 0x3c000000, v184
	v_mul_f32_e32 v30, 0x4b800000, v0
	v_cmp_gt_f32_e32 vcc, s90, v0
	v_mov_b32_e32 v73, v63
	v_mov_b32_e32 v71, v62
	v_cndmask_b32_e32 v0, v0, v30, vcc
	v_rsq_f32_e32 v0, v0
	s_brev_b32 s0, 60
	s_mov_b32 s30, 0
	v_mul_f32_e32 v28, 0x45800000, v0
	v_cndmask_b32_e32 v0, v0, v28, vcc
	v_mul_f32_e32 v0, 0x3db504f3, v0
	v_pk_mul_f32 v[28:29], v[0:1], v[56:57] op_sel_hi:[0,1]
	v_pk_mul_f32 v[30:31], v[0:1], v[36:37] op_sel_hi:[0,1]
	v_pk_mul_f32 v[36:37], v[0:1], v[54:55] op_sel_hi:[0,1]
	v_pk_mul_f32 v[52:53], v[0:1], v[52:53] op_sel_hi:[0,1]
	v_pk_mul_f32 v[28:29], v[22:23], v[28:29]
	v_pk_mul_f32 v[30:31], v[24:25], v[30:31]
	v_pk_mul_f32 v[36:37], v[18:19], v[36:37]
	v_pk_mul_f32 v[52:53], v[20:21], v[52:53]
	v_cvt_pk_bf16_f32 v28, v28, v29
	v_cvt_pk_bf16_f32 v29, v30, v31
	v_cvt_pk_bf16_f32 v30, v36, v37
	v_cvt_pk_bf16_f32 v31, v52, v53
	ds_write_b128 v58, v[28:31]
	v_mov_b64_e32 v[28:29], v[164:165]
	v_mov_b64_e32 v[30:31], v[166:167]
	v_and_b32_e32 v37, 0xffff0000, v26
	v_lshlrev_b32_e32 v34, 16, v27
	v_and_b32_e32 v35, 0xffff0000, v27
	v_lshlrev_b32_e32 v36, 16, v26
	v_mov_b32_e32 v72, v37
	v_pk_mul_f32 v[26:27], v[48:49], v[48:49]
	v_pk_mul_f32 v[52:53], v[60:61], v[60:61]
	v_pk_mul_f32 v[54:55], v[32:33], v[32:33]
	v_pk_mul_f32 v[56:57], v[64:65], v[64:65]
	v_pk_mul_f32 v[58:59], v[66:67], v[66:67]
	v_pk_mul_f32 v[68:69], v[34:35], v[34:35]
	v_mov_b32_e32 v70, v36
	v_pk_mul_f32 v[72:73], v[72:73], v[72:73]
	v_mov_b32_e32 v82, v68
	v_mov_b32_e32 v83, v54
	v_mov_b32_e32 v54, v69
	v_mov_b32_e32 v68, v58
	v_mov_b32_e32 v69, v52
	v_mov_b32_e32 v52, v59
	v_mov_b32_e32 v58, v56
	v_mov_b32_e32 v59, v26
	v_mov_b32_e32 v26, v57
	v_pk_fma_f32 v[56:57], v[70:71], v[70:71], v[72:73]
	s_waitcnt lgkmcnt(0)
	v_lshlrev_b32_e32 v72, 16, v28
	v_pk_add_f32 v[56:57], v[82:83], v[56:57]
	v_and_b32_e32 v73, 0xffff0000, v28
	v_pk_add_f32 v[54:55], v[54:55], v[56:57]
	v_add_u32_e32 v56, s33, v87
	v_pk_add_f32 v[54:55], v[68:69], v[54:55]
	v_ashrrev_i32_e32 v57, 31, v56
	v_pk_add_f32 v[52:53], v[52:53], v[54:55]
	v_add_u32_e32 v54, s33, v86
	v_pk_add_f32 v[52:53], v[58:59], v[52:53]
	v_ashrrev_i32_e32 v55, 31, v54
	v_pk_add_f32 v[26:27], v[26:27], v[52:53]
	s_nop 1
	v_mov_b32_dpp v53, v27 quad_perm:[1,0,3,2] row_mask:0xf bank_mask:0xf
	s_nop 1
	v_mov_b32_dpp v52, v26 quad_perm:[1,0,3,2] row_mask:0xf bank_mask:0xf
	v_lshlrev_b64 v[54:55], 8, v[54:55]
	v_lshl_add_u64 v[54:55], s[2:3], 0, v[54:55]
	v_lshl_add_u64 v[68:69], v[54:55], 0, v[76:77]
	v_lshl_add_u64 v[54:55], v[54:55], 0, v[78:79]
	s_waitcnt lgkmcnt(0)
	v_pk_add_f32 v[26:27], v[26:27], v[52:53]
	s_nop 1
	v_mov_b32_dpp v53, v27 quad_perm:[2,3,0,1] row_mask:0xf bank_mask:0xf
	s_nop 1
	v_mov_b32_dpp v52, v26 quad_perm:[2,3,0,1] row_mask:0xf bank_mask:0xf
	v_lshl_add_u64 v[68:69], v[68:69], 0, v[42:43]
	v_lshl_add_u64 v[70:71], v[54:55], 0, v[44:45]
	v_lshlrev_b32_e32 v54, 16, v31
	v_and_b32_e32 v55, 0xffff0000, v31
	s_waitcnt lgkmcnt(0)
	v_pk_add_f32 v[26:27], v[26:27], v[52:53]
	s_nop 1
	v_mov_b32_dpp v53, v27 row_shl:4 row_mask:0xf bank_mask:0x5
	v_mov_b32_dpp v53, v27 row_shr:4 row_mask:0xf bank_mask:0xa
	s_nop 1
	v_mov_b32_dpp v52, v26 row_shl:4 row_mask:0xf bank_mask:0x5
	v_mov_b32_dpp v52, v26 row_shr:4 row_mask:0xf bank_mask:0xa
	v_add_u32_e32 v58, s33, v88
	v_ashrrev_i32_e32 v59, 31, v58
	v_lshlrev_b64 v[56:57], 8, v[56:57]
	v_lshlrev_b64 v[58:59], 8, v[58:59]
	s_waitcnt lgkmcnt(0)
	v_pk_add_f32 v[26:27], v[26:27], v[52:53]
	s_nop 1
	v_mov_b32_dpp v53, v27 row_shl:8 row_mask:0xf bank_mask:0x3
	v_mov_b32_dpp v53, v27 row_shr:8 row_mask:0xf bank_mask:0xc
	s_nop 1
	v_mov_b32_dpp v52, v26 row_shl:8 row_mask:0xf bank_mask:0x3
	v_mov_b32_dpp v52, v26 row_shr:8 row_mask:0xf bank_mask:0xc
	v_lshl_add_u64 v[56:57], v[74:75], 0, v[56:57]
	v_lshl_add_u64 v[58:59], v[74:75], 0, v[58:59]
	s_movk_i32 s33, 0x800
	s_waitcnt lgkmcnt(0)
	v_pk_add_f32 v[26:27], v[26:27], v[52:53]
	s_nop 0
	v_pk_fma_f32 v[26:27], v[26:27], s[0:1], v[184:185] op_sel_hi:[1,0,0]
	s_nop 0
	v_mul_f32_e32 v0, 0x4b800000, v27
	v_cmp_gt_f32_e32 vcc, s90, v27
	v_mul_f32_e32 v42, 0x4b800000, v26
	v_cmp_gt_f32_e64 s[0:1], s90, v26
	v_cndmask_b32_e32 v0, v27, v0, vcc
	v_rsq_f32_e32 v0, v0
	v_cndmask_b32_e64 v26, v26, v42, s[0:1]
	v_mad_u64_u32 v[42:43], s[36:37], v98, s38, v[46:47]
	v_mul_f32_e32 v27, 0x45800000, v0
	v_cndmask_b32_e32 v0, v0, v27, vcc
	v_pk_mul_f32 v[44:45], v[0:1], v[62:63] op_sel_hi:[0,1]
	v_lshlrev_b32_e32 v62, 16, v29
	v_and_b32_e32 v63, 0xffff0000, v29
	v_pk_mul_f32 v[98:99], v[72:73], v[72:73]
	v_pk_mul_f32 v[32:33], v[0:1], v[32:33] op_sel_hi:[0,1]
	v_pk_mul_f32 v[52:53], v[0:1], v[60:61] op_sel_hi:[0,1]
	v_pk_mul_f32 v[48:49], v[0:1], v[48:49] op_sel_hi:[0,1]
	v_pk_mul_f32 v[82:83], v[62:63], v[62:63]
	v_add_f32_e32 v0, v98, v99
	v_lshlrev_b32_e32 v60, 16, v30
	v_and_b32_e32 v61, 0xffff0000, v30
	v_add_f32_e32 v0, v82, v0
	v_pk_mul_f32 v[30:31], v[60:61], v[60:61]
	v_add_f32_e32 v0, v83, v0
	v_add_f32_e32 v0, v30, v0
	v_pk_mul_f32 v[28:29], v[54:55], v[54:55]
	v_add_f32_e32 v0, v31, v0
	v_add_f32_e32 v0, v28, v0
	v_add_f32_e32 v0, v29, v0
	s_nop 1
	v_mov_b32_dpp v41, v0 quad_perm:[1,0,3,2] row_mask:0xf bank_mask:0xf
	v_rsq_f32_e32 v26, v26
	v_pk_mul_f32 v[32:33], v[8:9], v[32:33]
	v_pk_mul_f32 v[48:49], v[4:5], v[48:49]
	v_bfe_u32 v98, v39, 4, 2
	s_waitcnt lgkmcnt(0)
; __device__ __forceinline__ void tile_write(const TileRegs& t, unsigned char* buf, const f32x4& g0, const f32x4& g1, int tid, int lane) {
;     bf16_t* Ks = (bf16_t*)buf; bf16_t* VT = (bf16_t*)(buf + AT_VOFF);
; #pragma unroll
;     for (int i = 0; i < 2; ++i) {
;         const int idx = tid + 512 * i, r = idx >> 4, ch = idx & 15;
;         const u32x4 raw = t.k[i];
;         float v[8] = {bflo(raw[0]), bfhi(raw[0]), bflo(raw[1]), bfhi(raw[1]), bflo(raw[2]), bfhi(raw[2]), bflo(raw[3]), bfhi(raw[3])};
;         float ss = 0.f;
; #pragma unroll
;         for (int j = 0; j < 8; ++j) ss += v[j] * v[j];
;         ss += shx(ss, 1, lane); ss += shx(ss, 2, lane); ss += shx(ss, 4, lane); ss += shx(ss, 8, lane);
;         const float inv = rsqrtf(ss * (1.f / 128.f) + EPS);
;         u32x4 o = {pk2(v[0] * inv * g0[0], v[1] * inv * g0[1]), pk2(v[2] * inv * g0[2], v[3] * inv * g0[3]),
;                    pk2(v[4] * inv * g1[0], v[5] * inv * g1[1]), pk2(v[6] * inv * g1[2], v[7] * inv * g1[3])};
;         *(u32x4*)(Ks + r * 136 + ch * 8) = o;
;         const u32x4 rv = t.v[i];
;         bf16_t* d = VT + ((idx >> 6) * 8) * 72 + (idx & 63);
;         d[0] = (bf16_t)(rv[0] & 0xffff); d[72] = (bf16_t)(rv[0] >> 16); d[144] = (bf16_t)(rv[1] & 0xffff); d[216] = (bf16_t)(rv[1] >> 16);
;         d[288] = (bf16_t)(rv[2] & 0xffff); d[360] = (bf16_t)(rv[2] >> 16); d[432] = (bf16_t)(rv[3] & 0xffff); d[504] = (bf16_t)(rv[3] >> 16);
;     }
; }
; __device__ __forceinline__ void dil_item(const Params& p, int item, int l, unsigned char* lds) {
;     ...
;     const float slope = exp2f(-8.f * (float)(head + 1) / 6.f) * (float)r;
;     bf16_t* Qs = (bf16_t*)(lds + AT_Q);
;     const float* gq = p.in[9] + l * 128; const float* gk = p.in[10] + l * 128;
;     const f32x4 gk0 = *(const f32x4*)(gk + (tid & 15) * 8), gk1 = *(const f32x4*)(gk + (tid & 15) * 8 + 4);
;     const int kcol = C_KDIL + head * 128, vcol = C_VDIL + head * 128;
;     __syncthreads();
;     TileRegs tr;
;     int c = n == 0 ? 2 : 0;
;     tile_load(tr, P, (128 * (n - 1) + 64 * c) * r + rho, r, kcol, vcol, tid);
;     stage_rows128_norm(Qs, P, (128 * n) * r + rho, r, C_QDIL + head * 128, gq, 0.08838834764831845f);
;     tile_write(tr, lds + AT_BUF, gk0, gk1, tid, lane);
;     tile_load(tr, P, (128 * (n - 1) + 64 * (c + 1)) * r + rho, r, kcol, vcol, tid);
;     __syncthreads();
;     bf16x8 qf[4];
; #pragma unroll
	v_add_f32_e32 v0, v0, v41
	s_nop 1
	v_mov_b32_dpp v41, v0 quad_perm:[2,3,0,1] row_mask:0xf bank_mask:0xf
	v_mul_f32_e32 v43, 0x45800000, v26
	v_cndmask_b32_e64 v26, v26, v43, s[0:1]
	v_pk_mul_f32 v[30:31], v[26:27], v[66:67] op_sel_hi:[0,1]
	v_pk_mul_f32 v[28:29], v[26:27], v[34:35] op_sel_hi:[0,1]
	s_waitcnt lgkmcnt(0)
	v_add_f32_e32 v0, v0, v41
	s_nop 1
	v_mov_b32_dpp v41, v0 row_shl:4 row_mask:0xf bank_mask:0x5
	v_mov_b32_dpp v41, v0 row_shr:4 row_mask:0xf bank_mask:0xa
	v_pk_mul_f32 v[34:35], v[6:7], v[44:45]
	v_pk_mul_f32 v[44:45], v[2:3], v[52:53]
	v_pk_mul_f32 v[52:53], v[2:3], v[30:31]
	v_pk_mul_f32 v[36:37], v[26:27], v[36:37] op_sel_hi:[0,1]
	s_waitcnt lgkmcnt(0)
	v_add_f32_e32 v0, v0, v41
	s_nop 1
	v_mov_b32_dpp v31, v0 row_shl:8 row_mask:0xf bank_mask:0x3
	v_mov_b32_dpp v31, v0 row_shr:8 row_mask:0xf bank_mask:0xc
	v_pk_mul_f32 v[26:27], v[26:27], v[64:65] op_sel_hi:[0,1]
	v_pk_mul_f32 v[64:65], v[4:5], v[26:27]
	v_cvt_pk_bf16_f32 v26, v34, v35
	v_pk_mul_f32 v[36:37], v[6:7], v[36:37]
	s_waitcnt lgkmcnt(0)
	v_add_f32_e32 v0, v0, v31
	v_fmamk_f32 v0, v0, 0x3c000000, v184
	v_mul_f32_e32 v31, 0x4b800000, v0
	v_cmp_gt_f32_e32 vcc, s90, v0
	v_pk_mul_f32 v[50:51], v[8:9], v[28:29]
	v_cvt_pk_bf16_f32 v28, v44, v45
	v_cndmask_b32_e32 v0, v0, v31, vcc
	v_rsq_f32_e32 v0, v0
	v_cvt_pk_bf16_f32 v30, v36, v37
	v_cvt_pk_bf16_f32 v27, v32, v33
	v_cvt_pk_bf16_f32 v29, v48, v49
	v_mul_f32_e32 v34, 0x45800000, v0
	v_cndmask_b32_e32 v0, v0, v34, vcc
	v_mul_f32_e32 v0, 0x3db504f3, v0
	v_pk_mul_f32 v[34:35], v[0:1], v[72:73] op_sel_hi:[0,1]
	v_pk_mul_f32 v[36:37], v[0:1], v[62:63] op_sel_hi:[0,1]
	v_pk_mul_f32 v[44:45], v[0:1], v[60:61] op_sel_hi:[0,1]
	v_pk_mul_f32 v[46:47], v[0:1], v[54:55] op_sel_hi:[0,1]
	v_pk_mul_f32 v[22:23], v[22:23], v[34:35]
	v_pk_mul_f32 v[24:25], v[24:25], v[36:37]
	v_pk_mul_f32 v[34:35], v[18:19], v[44:45]
	v_pk_mul_f32 v[36:37], v[20:21], v[46:47]
	v_cvt_pk_bf16_f32 v18, v22, v23
	v_cvt_pk_bf16_f32 v19, v24, v25
	v_cvt_pk_bf16_f32 v20, v34, v35
	v_cvt_pk_bf16_f32 v21, v36, v37
	v_cvt_pk_bf16_f32 v31, v50, v51
	v_cvt_pk_bf16_f32 v32, v52, v53
	v_cvt_pk_bf16_f32 v33, v64, v65
	ds_write_b128 v42, v[18:21]
	ds_write_b128 v100, v[26:29] offset:34816
	ds_write_b16 v81, v14 offset:52224
	ds_write_b16_d16_hi v81, v14 offset:52368
	ds_write_b16 v81, v15 offset:52512
	ds_write_b16_d16_hi v81, v15 offset:52656
	ds_write_b16 v81, v16 offset:52800
	ds_write_b16_d16_hi v81, v16 offset:52944
	ds_write_b16 v81, v17 offset:53088
	ds_write_b16_d16_hi v81, v17 offset:53232
	ds_write_b128 v102, v[30:33] offset:34816
	ds_write_b16 v103, v10 offset:52224
	ds_write_b16_d16_hi v103, v10 offset:52368
	ds_write_b16 v103, v11 offset:52512
	ds_write_b16_d16_hi v103, v11 offset:52656
	ds_write_b16 v103, v12 offset:52800
	ds_write_b16_d16_hi v103, v12 offset:52944
	ds_write_b16 v103, v13 offset:53088
	ds_write_b16_d16_hi v103, v13 offset:53232
	flat_load_dwordx4 v[42:45], v[56:57]
	s_nop 0
	flat_load_dwordx4 v[54:57], v[68:69]
	s_nop 0
	flat_load_dwordx4 v[66:69], v[58:59]
	s_nop 0
	flat_load_dwordx4 v[70:73], v[70:71]
	v_fma_f32 v0, -v104, v105, 1.0
	v_fmac_f32_e32 v105, v0, v105
	v_div_scale_f32 v0, vcc, v101, s39, v101
	v_mul_f32_e32 v10, v0, v105
	v_fma_f32 v11, -v104, v10, v0
	v_fmac_f32_e32 v10, v11, v105
	v_fma_f32 v0, -v104, v10, v0
	v_ashrrev_i32_e32 v11, 2, v39
	v_div_fmas_f32 v0, v0, v105, v10
	v_bfi_b32 v99, -16, v11, v39
	v_div_fixup_f32 v0, v0, s39, v101
	v_and_b32_e32 v12, -16, v11
	v_mul_lo_u32 v11, v99, s38
	v_and_b32_e32 v100, 48, v39
	s_mov_b32 s0, 0xc2fc0000
	v_add3_u32 v11, 0, v11, v100
	v_cmp_gt_f32_e32 vcc, s0, v0
	s_waitcnt lgkmcnt(0)
	s_barrier
	ds_read_b128 v[46:49], v11
	ds_read_b128 v[50:53], v11 offset:64
	ds_read_b128 v[58:61], v11 offset:128
	ds_read_b128 v[62:65], v11 offset:192
	v_cndmask_b32_e32 v11, 0, v216, vcc
	v_add_f32_e32 v0, v0, v11
	v_exp_f32_e32 v0, v0
	s_and_b64 s[0:1], vcc, exec
	s_cselect_b32 s0, 0xffffffc0, 0
	v_cvt_f32_ubyte0_e32 v10, s31
	v_ldexp_f32 v0, v0, s0
	v_mul_f32_e32 v101, v0, v10
	v_mul_i32_i24_e32 v0, -4, v98
	v_add3_u32 v0, v0, v12, v80
	v_subrev_u32_e32 v0, s28, v0
	v_add_u32_e32 v102, 0x8f, v12
	v_lshlrev_b32_e32 v103, 3, v98
	v_mul_u32_u24_e32 v104, 0x90, v80
	v_subrev_u32_e32 v105, 63, v12
	v_add_u32_e32 v107, 0x4d, v0
	v_lshlrev_b32_e32 v80, 1, v38
	v_lshlrev_b32_e32 v82, 1, v40
	v_mov_b32_e32 v34, 0
	v_mov_b32_e32 v35, v108
	v_mov_b32_e32 v36, v108
	v_mov_b32_e32 v37, v108
	v_mov_b32_e32 v38, v108
	v_mov_b32_e32 v39, v108
	v_mov_b32_e32 v40, v108
	v_mov_b32_e32 v41, v108
	v_mov_b32_e32 v30, v108
	v_mov_b32_e32 v31, v108
	v_mov_b32_e32 v32, v108
	v_mov_b32_e32 v33, v108
	v_mov_b32_e32 v26, v108
	v_mov_b32_e32 v27, v108
	v_mov_b32_e32 v28, v108
	v_mov_b32_e32 v29, v108
	v_mov_b32_e32 v22, v108
	v_mov_b32_e32 v23, v108
	v_mov_b32_e32 v24, v108
	v_mov_b32_e32 v25, v108
	v_mov_b32_e32 v18, v108
	v_mov_b32_e32 v19, v108
	v_mov_b32_e32 v20, v108
	v_mov_b32_e32 v21, v108
	v_mov_b32_e32 v14, v108
	v_mov_b32_e32 v15, v108
	v_mov_b32_e32 v16, v108
	v_mov_b32_e32 v17, v108
	v_mov_b32_e32 v10, v108
	v_mov_b32_e32 v11, v108
	v_mov_b32_e32 v12, v108
	v_mov_b32_e32 v13, v108
	s_branch .LBB0_110

; __device__ __forceinline__ unsigned pk2(float lo, float hi) { const f32v2_t v = {lo, hi}; return __builtin_bit_cast(unsigned, __builtin_convertvector(v, bf16v2_t)); }
; __device__ __forceinline__ float shx(float v, int mask, int lane) { return __int_as_float(__builtin_amdgcn_ds_bpermute((lane ^ mask) << 2, __float_as_int(v))); }
; __device__ __forceinline__ float bflo(unsigned u) { return __uint_as_float(u << 16); }
; __device__ __forceinline__ float bfhi(unsigned u) { return __uint_as_float(u & 0xffff0000u); }
; __device__ __forceinline__ void tile_write(const TileRegs& t, unsigned char* buf, const f32x4& g0, const f32x4& g1, int tid, int lane) {
;     bf16_t* Ks = (bf16_t*)buf; bf16_t* VT = (bf16_t*)(buf + AT_VOFF);
; #pragma unroll
;     for (int i = 0; i < 2; ++i) {
;         const int idx = tid + 512 * i, r = idx >> 4, ch = idx & 15;
;         const u32x4 raw = t.k[i];
;         float v[8] = {bflo(raw[0]), bfhi(raw[0]), bflo(raw[1]), bfhi(raw[1]), bflo(raw[2]), bfhi(raw[2]), bflo(raw[3]), bfhi(raw[3])};
;         float ss = 0.f;
; #pragma unroll
;         for (int j = 0; j < 8; ++j) ss += v[j] * v[j];
;         ss += shx(ss, 1, lane); ss += shx(ss, 2, lane); ss += shx(ss, 4, lane); ss += shx(ss, 8, lane);
;         const float inv = rsqrtf(ss * (1.f / 128.f) + EPS);
;         u32x4 o = {pk2(v[0] * inv * g0[0], v[1] * inv * g0[1]), pk2(v[2] * inv * g0[2], v[3] * inv * g0[3]),
;                    pk2(v[4] * inv * g1[0], v[5] * inv * g1[1]), pk2(v[6] * inv * g1[2], v[7] * inv * g1[3])};
;         *(u32x4*)(Ks + r * 136 + ch * 8) = o;
;         const u32x4 rv = t.v[i];
;         bf16_t* d = VT + ((idx >> 6) * 8) * 72 + (idx & 63);
;         d[0] = (bf16_t)(rv[0] & 0xffff); d[72] = (bf16_t)(rv[0] >> 16); d[144] = (bf16_t)(rv[1] & 0xffff); d[216] = (bf16_t)(rv[1] >> 16);
;         d[288] = (bf16_t)(rv[2] & 0xffff); d[360] = (bf16_t)(rv[2] >> 16); d[432] = (bf16_t)(rv[3] & 0xffff); d[504] = (bf16_t)(rv[3] >> 16);
;     }
; }
; __device__ __forceinline__ void dil_item(const Params& p, int item, int l, unsigned char* lds) {
;     ...
;             pv_tile(oacc, VT, 72, 0, wgt, fr, fq);
;         }
;         if (c == 3) break;
;         tile_write(tr, lds + AT_BUF + (cur ^ 1) * AT_BUFSZ, gk0, gk1, tid, lane);
;         if (c + 2 <= 3) tile_load(tr, P, (128 * (n - 1) + 64 * (c + 2)) * r + rho, r, kcol, vcol, tid);
;         __syncthreads();
.LBB0_112:
	s_or_b64 exec, exec, s[0:1]
	s_cmp_eq_u32 s25, 3
	s_cbranch_scc1 .LBB0_115
	s_waitcnt vmcnt(0)
	v_and_b32_e32 v123, 0xffff0000, v42
	v_and_b32_e32 v137, 0xffff0000, v66
	v_lshlrev_b32_e32 v118, 16, v43
	v_and_b32_e32 v119, 0xffff0000, v43
	v_lshlrev_b32_e32 v122, 16, v42
	v_lshlrev_b32_e32 v132, 16, v67
	v_and_b32_e32 v133, 0xffff0000, v67
	v_lshlrev_b32_e32 v136, 16, v66
	v_mov_b32_e32 v140, v137
	v_mov_b32_e32 v141, v123
	v_pk_mul_f32 v[120:121], v[118:119], v[118:119]
	v_pk_mul_f32 v[134:135], v[132:133], v[132:133]
	v_mov_b32_e32 v138, v136
	v_mov_b32_e32 v139, v122
	v_pk_mul_f32 v[140:141], v[140:141], v[140:141]
	v_lshlrev_b32_e32 v112, 16, v44
	v_and_b32_e32 v113, 0xffff0000, v44
	v_lshlrev_b32_e32 v128, 16, v68
	v_and_b32_e32 v129, 0xffff0000, v68
	v_pk_fma_f32 v[138:139], v[138:139], v[138:139], v[140:141]
	v_mov_b32_e32 v140, v134
	v_mov_b32_e32 v141, v120
	v_pk_mul_f32 v[116:117], v[112:113], v[112:113]
	v_pk_mul_f32 v[130:131], v[128:129], v[128:129]
	v_pk_add_f32 v[138:139], v[140:141], v[138:139]
	v_mov_b32_e32 v120, v135
	v_lshlrev_b32_e32 v114, 16, v45
	v_and_b32_e32 v115, 0xffff0000, v45
	v_lshlrev_b32_e32 v124, 16, v69
	v_and_b32_e32 v125, 0xffff0000, v69
	v_pk_add_f32 v[120:121], v[120:121], v[138:139]
	v_mov_b32_e32 v134, v130
	v_mov_b32_e32 v135, v116
	v_pk_mul_f32 v[110:111], v[114:115], v[114:115]
	v_pk_mul_f32 v[126:127], v[124:125], v[124:125]
	v_pk_add_f32 v[120:121], v[134:135], v[120:121]
	v_mov_b32_e32 v116, v131
	v_pk_add_f32 v[116:117], v[116:117], v[120:121]
	v_mov_b32_e32 v120, v126
	v_mov_b32_e32 v121, v110
	v_pk_add_f32 v[116:117], v[120:121], v[116:117]
	v_mov_b32_e32 v110, v127
	v_pk_add_f32 v[110:111], v[110:111], v[116:117]
	s_nop 1
	v_mov_b32_dpp v117, v111 quad_perm:[1,0,3,2] row_mask:0xf bank_mask:0xf
	s_nop 1
	v_mov_b32_dpp v116, v110 quad_perm:[1,0,3,2] row_mask:0xf bank_mask:0xf
	s_brev_b32 s36, 60
	s_xor_b32 s30, s30, 1
	s_mul_i32 s0, s30, 0x8c00
	s_add_i32 s0, s0, 0
	s_waitcnt lgkmcnt(0)
	v_pk_add_f32 v[110:111], v[110:111], v[116:117]
	s_nop 1
	v_mov_b32_dpp v117, v111 quad_perm:[2,3,0,1] row_mask:0xf bank_mask:0xf
	s_nop 1
	v_mov_b32_dpp v116, v110 quad_perm:[2,3,0,1] row_mask:0xf bank_mask:0xf
	v_lshl_add_u32 v81, v85, 1, s0
	v_lshl_add_u32 v83, v84, 1, s0
	v_lshl_add_u32 v109, v90, 1, v81
	s_cmp_gt_u32 s25, 1
	s_waitcnt lgkmcnt(0)
	v_pk_add_f32 v[110:111], v[110:111], v[116:117]
	s_nop 1
	v_mov_b32_dpp v117, v111 row_shl:4 row_mask:0xf bank_mask:0x5
	v_mov_b32_dpp v117, v111 row_shr:4 row_mask:0xf bank_mask:0xa
	s_nop 1
	v_mov_b32_dpp v116, v110 row_shl:4 row_mask:0xf bank_mask:0x5
	v_mov_b32_dpp v116, v110 row_shr:4 row_mask:0xf bank_mask:0xa
	s_waitcnt lgkmcnt(0)
	v_pk_add_f32 v[110:111], v[110:111], v[116:117]
	s_nop 1
	v_mov_b32_dpp v117, v111 row_shl:8 row_mask:0xf bank_mask:0x3
	v_mov_b32_dpp v117, v111 row_shr:8 row_mask:0xf bank_mask:0xc
	s_nop 1
	v_mov_b32_dpp v116, v110 row_shl:8 row_mask:0xf bank_mask:0x3
	v_mov_b32_dpp v116, v110 row_shr:8 row_mask:0xf bank_mask:0xc
	s_waitcnt lgkmcnt(0)
	v_pk_add_f32 v[110:111], v[110:111], v[116:117]
	s_nop 0
	v_pk_fma_f32 v[116:117], v[110:111], s[36:37], v[184:185] op_sel_hi:[1,0,0]
	s_nop 0
	v_mul_f32_e32 v0, 0x4b800000, v117
	v_cmp_gt_f32_e32 vcc, s90, v117
	s_nop 1
	v_cndmask_b32_e32 v0, v117, v0, vcc
	v_rsq_f32_e32 v0, v0
	v_lshl_add_u32 v117, v95, 1, v83
	v_mul_f32_e32 v110, 0x45800000, v0
	v_cndmask_b32_e32 v0, v0, v110, vcc
	v_pk_mul_f32 v[110:111], v[0:1], v[122:123] op_sel_hi:[0,1]
	v_pk_mul_f32 v[118:119], v[0:1], v[118:119] op_sel_hi:[0,1]
	v_pk_mul_f32 v[112:113], v[0:1], v[112:113] op_sel_hi:[0,1]
	v_pk_mul_f32 v[114:115], v[0:1], v[114:115] op_sel_hi:[0,1]
	v_mul_f32_e32 v0, 0x4b800000, v116
	v_cmp_gt_f32_e32 vcc, s90, v116
	v_pk_mul_f32 v[110:111], v[6:7], v[110:111]
	v_pk_mul_f32 v[118:119], v[8:9], v[118:119]
	v_cndmask_b32_e32 v0, v116, v0, vcc
	v_rsq_f32_e32 v0, v0
	v_pk_mul_f32 v[112:113], v[2:3], v[112:113]
	v_pk_mul_f32 v[114:115], v[4:5], v[114:115]
	v_cvt_pk_bf16_f32 v110, v110, v111
	v_cvt_pk_bf16_f32 v111, v118, v119
	v_cvt_pk_bf16_f32 v112, v112, v113
	v_cvt_pk_bf16_f32 v113, v114, v115
	ds_write_b128 v109, v[110:113] offset:34816
	ds_write_b16 v117, v54 offset:52224
	ds_write_b16_d16_hi v117, v54 offset:52368
	ds_write_b16 v117, v55 offset:52512
	ds_write_b16_d16_hi v117, v55 offset:52656
	ds_write_b16 v117, v56 offset:52800
	v_mul_f32_e32 v109, 0x45800000, v0
	v_cndmask_b32_e32 v0, v0, v109, vcc
	v_pk_mul_f32 v[110:111], v[0:1], v[136:137] op_sel_hi:[0,1]
	v_pk_mul_f32 v[112:113], v[0:1], v[132:133] op_sel_hi:[0,1]
	v_pk_mul_f32 v[110:111], v[6:7], v[110:111]
	v_pk_mul_f32 v[112:113], v[8:9], v[112:113]
	v_cvt_pk_bf16_f32 v110, v110, v111
	v_cvt_pk_bf16_f32 v111, v112, v113
	v_pk_mul_f32 v[112:113], v[0:1], v[128:129] op_sel_hi:[0,1]
	v_pk_mul_f32 v[114:115], v[0:1], v[124:125] op_sel_hi:[0,1]
	v_pk_mul_f32 v[112:113], v[2:3], v[112:113]
	v_pk_mul_f32 v[114:115], v[4:5], v[114:115]
	v_cvt_pk_bf16_f32 v112, v112, v113
	v_cvt_pk_bf16_f32 v113, v114, v115
	v_lshl_add_u32 v0, v96, 1, v81
	ds_write_b16_d16_hi v117, v56 offset:52944
	ds_write_b16 v117, v57 offset:53088
	ds_write_b16_d16_hi v117, v57 offset:53232
	ds_write_b128 v0, v[110:113] offset:34816
	v_lshl_add_u32 v0, v97, 1, v83
	ds_write_b16 v0, v70 offset:52224
	ds_write_b16_d16_hi v0, v70 offset:52368
	ds_write_b16 v0, v71 offset:52512
	ds_write_b16_d16_hi v0, v71 offset:52656
	ds_write_b16 v0, v72 offset:52800
	ds_write_b16_d16_hi v0, v72 offset:52944
	ds_write_b16 v0, v73 offset:53088
	ds_write_b16_d16_hi v0, v73 offset:53232
	s_cbranch_scc1 .LBB0_109
	s_add_i32 s0, s19, s28
	s_lshl_b32 s0, s0, s17
	s_or_b32 s0, s0, s18
	v_add_u32_e32 v0, s0, v86
	v_lshlrev_b64 v[42:43], 8, v[0:1]
	v_lshl_add_u64 v[66:67], s[2:3], 0, v[42:43]
	v_add_u32_e32 v42, s0, v87
	v_add_u32_e32 v68, s0, v88
	v_ashrrev_i32_e32 v43, 31, v42
	v_ashrrev_i32_e32 v69, 31, v68
	v_lshlrev_b64 v[42:43], 8, v[42:43]
	v_lshl_add_u64 v[44:45], v[66:67], 0, v[76:77]
	v_mov_b32_e32 v81, v1
	v_lshlrev_b64 v[68:69], 8, v[68:69]
	v_lshl_add_u64 v[66:67], v[66:67], 0, v[78:79]
	v_mov_b32_e32 v83, v1
	v_lshl_add_u64 v[42:43], v[74:75], 0, v[42:43]
	v_lshl_add_u64 v[54:55], v[44:45], 0, v[80:81]
	v_lshl_add_u64 v[68:69], v[74:75], 0, v[68:69]
	v_lshl_add_u64 v[70:71], v[66:67], 0, v[82:83]
	flat_load_dwordx4 v[42:45], v[42:43]
	s_nop 0
	flat_load_dwordx4 v[54:57], v[54:55]
	s_nop 0
	flat_load_dwordx4 v[66:69], v[68:69]
	s_nop 0
	flat_load_dwordx4 v[70:73], v[70:71]
	s_branch .LBB0_109

; __device__ __forceinline__ int tidx() { int t = threadIdx.x; asm volatile("" : "+v"(t)); return t; }
; __device__ __forceinline__ float shx(float v, int mask, int lane) { return __int_as_float(__builtin_amdgcn_ds_bpermute((lane ^ mask) << 2, __float_as_int(v))); }
; __device__ __forceinline__ size_t pidx(int row, int col) { return (size_t)(col >> 7) * ((size_t)T * 128) + (size_t)row * 128 + (col & 127); }
; __device__ __forceinline__ void stage_rows128_norm(bf16_t* dst, const bf16_t* P, int r0, int rstride, int col, const float* __restrict__ gain, float qs) {
;     const int tid = tidx(), lane = tid & 63;
;     const f32x4 g0 = *(const f32x4*)(gain + (tid & 15) * 8), g1 = *(const f32x4*)(gain + (tid & 15) * 8 + 4);
; #pragma unroll
;     for (int i = 0; i < 4; ++i) {
;         const int idx = tid + 512 * i, r = idx >> 4, ch = idx & 15;
;         const u32x4 raw = *(const u32x4*)(P + pidx(r0 + r * rstride, col + ch * 8));
;         float v[8] = {bflo(raw[0]), bfhi(raw[0]), bflo(raw[1]), bfhi(raw[1]), bflo(raw[2]), bfhi(raw[2]), bflo(raw[3]), bfhi(raw[3])};
;         float ss = 0.f;
; #pragma unroll
;         for (int j = 0; j < 8; ++j) ss += v[j] * v[j];
;         ss += shx(ss, 1, lane); ss += shx(ss, 2, lane); ss += shx(ss, 4, lane); ss += shx(ss, 8, lane);
;         const float inv = rsqrtf(ss * (1.f / 128.f) + EPS) * qs;
; __device__ __forceinline__ void sb_item(const Params& p, int item, int l, unsigned char* lds) {
;     const int tid = tidx(), w = tid >> 6, lane = tid & 63, fr = lane & 15, fq = lane >> 4;
;     const bf16_t* P = (const bf16_t*)(p.ws + W_PROJ);
;     bf16_t* OSB = (bf16_t*)(p.ws + W_OCAT);
;     const int head = item >> 6, I = 63 - (item & 63);
;     bf16_t* Qs = (bf16_t*)(lds + AT_Q); float* flags = (float*)(lds + AT_F);
;     const float* gq = p.in[7] + l * 128; const float* gk = p.in[8] + l * 128;
;     const f32x4 gk0 = *(const f32x4*)(gk + (tid & 15) * 8), gk1 = *(const f32x4*)(gk + (tid & 15) * 8 + 4);
;     const int kcol = C_KSB + head * 128, vcol = C_VSB + head * 128;
;     __syncthreads();
;     TileRegs tr;
;     int J = 2 * I + 1;
;     tile_load(tr, P, 64 * J, 1, kcol, vcol, tid);
;     stage_rows128_norm(Qs, P, 128 * I, 1, C_QSB + head * 128, gq, 0.08838834764831845f);
;     tile_write(tr, lds + AT_BUF, gk0, gk1, tid, lane);
;     tile_load(tr, P, 64 * (J - 1), 1, kcol, vcol, tid);
.LBB0_120:
	s_andn2_b64 vcc, exec, s[0:1]
	s_cbranch_vccnz .LBB0_84
	s_and_b32 s0, s13, 63
	v_mov_b32_e32 v52, v185
	s_lshl_b32 s1, s0, 1
	s_or_b32 s16, s1, 1
	v_lshlrev_b32_e32 v0, 3, v52
	v_and_b32_e32 v96, 0x78, v0
	v_readlane_b32 s4, v245, 55
	s_lshl_b32 s1, s15, 1
	s_lshl_b32 s17, s0, 7
	s_andn2_b32 s0, 63, s15
	v_lshlrev_b32_e32 v0, 2, v96
	v_readlane_b32 s5, v245, 56
	s_and_b32 s74, s1, 0xffffff80
	s_addk_i32 s1, 0x300
	s_nop 2
	global_load_dwordx4 v[2:5], v0, s[4:5] offset:16
	global_load_dwordx4 v[6:9], v0, s[4:5]
	s_lshl_b32 s4, s0, 7
	s_ashr_i32 s0, s1, 7
	s_ashr_i32 s1, s0, 31
	v_ashrrev_i32_e32 v72, 3, v52
	s_waitcnt vmcnt(2)
	v_add_u32_e32 v20, 0x200, v52
	s_add_i32 s5, s74, 0x600
	s_or_b32 s18, s4, 64
	s_lshl_b64 s[44:45], s[0:1], 21
	v_lshlrev_b32_e32 v16, 1, v72
	v_ashrrev_i32_e32 v54, 4, v20
	s_add_u32 s0, s2, s44
	v_and_b32_e32 v44, 0xf0, v16
	v_add_u32_e32 v16, s18, v54
	s_addc_u32 s1, s3, s45
	v_lshlrev_b32_e32 v0, 1, v96
	v_ashrrev_i32_e32 v17, 31, v16
	v_lshl_add_u64 v[38:39], s[0:1], 0, v[0:1]
	v_lshlrev_b64 v[16:17], 8, v[16:17]
	v_ashrrev_i32_e32 v61, 3, v20
	v_and_b32_e32 v87, 63, v52
	v_add_u32_e32 v14, s5, v72
	v_lshl_add_u64 v[18:19], v[38:39], 0, v[16:17]
	v_add_u32_e32 v16, s5, v61
	v_or_b32_e32 v10, s18, v87
	v_ashrrev_i32_e32 v53, 4, v52
	v_ashrrev_i32_e32 v14, 7, v14
	v_ashrrev_i32_e32 v16, 7, v16
	v_lshlrev_b32_e32 v10, 8, v10
	v_mov_b32_e32 v11, v1
	v_add_u32_e32 v12, s18, v53
	v_ashrrev_i32_e32 v15, 31, v14
	v_ashrrev_i32_e32 v17, 31, v16
	v_lshl_add_u64 v[10:11], s[2:3], 0, v[10:11]
	v_ashrrev_i32_e32 v13, 31, v12
	v_lshlrev_b64 v[42:43], 21, v[14:15]
	v_lshlrev_b64 v[46:47], 21, v[16:17]
	v_lshlrev_b32_e32 v16, 1, v61
	v_lshlrev_b64 v[12:13], 8, v[12:13]
	v_lshl_add_u64 v[14:15], v[10:11], 0, v[42:43]
	v_mov_b32_e32 v45, v1
	v_lshl_add_u64 v[10:11], v[10:11], 0, v[46:47]
	v_and_b32_e32 v48, 0xf0, v16
	v_mov_b32_e32 v49, v1
	s_ashr_i32 s0, s15, 6
	v_lshl_add_u64 v[12:13], v[38:39], 0, v[12:13]
	v_lshl_add_u64 v[14:15], v[14:15], 0, v[44:45]
	v_lshl_add_u64 v[10:11], v[10:11], 0, v[48:49]
	v_mov_b32_e32 v60, v185
	s_ashr_i32 s1, s0, 31
	s_waitcnt lgkmcnt(0)
	s_barrier
	flat_load_dwordx4 v[30:33], v[12:13]
	s_nop 0
	flat_load_dwordx4 v[14:17], v[14:15]
	s_nop 0
	flat_load_dwordx4 v[26:29], v[18:19]
	s_nop 0
	flat_load_dwordx4 v[10:13], v[10:11]
	s_lshl_b64 s[0:1], s[0:1], 21
	v_lshlrev_b32_e32 v18, 3, v60
	v_ashrrev_i32_e32 v70, 4, v60
	v_and_b32_e32 v20, 0x78, v18
	s_add_u32 s0, s2, s0
	v_add_u32_e32 v18, s4, v70
	s_addc_u32 s1, s3, s1
	v_lshlrev_b32_e32 v40, 1, v20
	v_mov_b32_e32 v41, v1
	v_ashrrev_i32_e32 v19, 31, v18
	v_lshl_add_u64 v[50:51], s[0:1], 0, v[40:41]
	v_lshlrev_b64 v[18:19], 8, v[18:19]
	v_lshl_add_u64 v[18:19], v[50:51], 0, v[18:19]
	flat_load_dwordx4 v[34:37], v[18:19]
	s_mov_b64 s[0:1], 0x2000
	v_lshl_add_u64 v[152:153], v[18:19], 0, s[0:1]
	flat_load_dwordx4 v[156:159], v[152:153]
	v_lshl_add_u64 v[152:153], v[152:153], 0, s[0:1]
	flat_load_dwordx4 v[160:163], v[152:153]
	v_lshl_add_u64 v[152:153], v[152:153], 0, s[0:1]
	flat_load_dwordx4 v[164:167], v[152:153]
	v_readlane_b32 s0, v245, 53
	v_lshlrev_b32_e32 v18, 2, v20
	v_readlane_b32 s1, v245, 54
	s_nop 4
	global_load_dwordx4 v[22:25], v18, s[0:1]
	s_nop 0
	global_load_dwordx4 v[18:21], v18, s[0:1] offset:16
	v_lshlrev_b32_e32 v55, 2, v60
	v_bitop3_b32 v41, v55, 4, v211 bitop3:0x6c
	v_add_u32_e32 v40, 0, v40
	s_movk_i32 s5, 0x110
	v_add_u32_e32 v92, 0, v0
	v_lshlrev_b32_e32 v90, 2, v87
	v_xor_b32_e32 v98, 4, v90
	v_xor_b32_e32 v99, 8, v90
	v_xor_b32_e32 v100, 16, v90
	v_xor_b32_e32 v101, 32, v90
	v_or_b32_e32 v91, s4, v87
	s_brev_b32 s76, 60
	s_movk_i32 s18, 0x48
	v_lshl_add_u32 v86, v87, 1, 0
	v_and_b32_e32 v105, 48, v52
	v_xor_b32_e32 v108, 64, v90
	v_xor_b32_e32 v109, 0x80, v90
	v_xor_b32_e32 v110, 0xc0, v90
	s_movk_i32 s78, 0xc000
	v_cmp_eq_u32_e64 s[36:37], 0, v87
	v_cmp_lt_u32_e64 s[38:39], 15, v87
	v_mov_b32_e32 v114, 1.0
	s_mov_b32 s25, 0xc2a00000
	s_mov_b32 s79, -1
	s_waitcnt vmcnt(0) lgkmcnt(0)
	v_and_b32_e32 v79, 0xffff0000, v28
	v_lshlrev_b32_e32 v68, 16, v34
	v_and_b32_e32 v69, 0xffff0000, v34
	v_lshlrev_b32_e32 v58, 16, v37
	v_and_b32_e32 v59, 0xffff0000, v37
	v_lshlrev_b32_e32 v62, 16, v36
	v_and_b32_e32 v63, 0xffff0000, v36
	v_lshlrev_b32_e32 v36, 16, v35
	v_and_b32_e32 v37, 0xffff0000, v35
	v_pk_mul_f32 v[34:35], v[68:69], v[68:69]
	v_pk_mul_f32 v[66:67], v[36:37], v[36:37]
	v_add_f32_e32 v34, v34, v35
	v_add_f32_e32 v34, v66, v34
	v_pk_mul_f32 v[64:65], v[62:63], v[62:63]
	v_add_f32_e32 v34, v67, v34
	v_add_f32_e32 v34, v64, v34
	v_pk_mul_f32 v[56:57], v[58:59], v[58:59]
	v_add_f32_e32 v34, v65, v34
	v_add_f32_e32 v34, v56, v34
	v_add_f32_e32 v34, v57, v34
	s_nop 1
	v_mov_b32_dpp v35, v34 quad_perm:[1,0,3,2] row_mask:0xf bank_mask:0xf
	v_bitop3_b32 v57, v55, 8, v211 bitop3:0x6c
	v_bitop3_b32 v56, v55, 16, v211 bitop3:0x6c
	v_bitop3_b32 v55, v55, 32, v211 bitop3:0x6c
	s_waitcnt lgkmcnt(0)
	v_add_f32_e32 v34, v34, v35
	s_nop 1
	v_mov_b32_dpp v35, v34 quad_perm:[2,3,0,1] row_mask:0xf bank_mask:0xf
	s_waitcnt lgkmcnt(0)
	v_add_f32_e32 v34, v34, v35
	s_nop 1
	v_mov_b32_dpp v35, v34 row_shl:4 row_mask:0xf bank_mask:0x5
	v_mov_b32_dpp v35, v34 row_shr:4 row_mask:0xf bank_mask:0xa
	s_waitcnt lgkmcnt(0)
	v_add_f32_e32 v34, v34, v35
	s_nop 1
	v_mov_b32_dpp v35, v34 row_shl:8 row_mask:0xf bank_mask:0x3
	v_mov_b32_dpp v35, v34 row_shr:8 row_mask:0xf bank_mask:0xc
	s_waitcnt lgkmcnt(0)
; __device__ __forceinline__ unsigned pk2(float lo, float hi) { const f32v2_t v = {lo, hi}; return __builtin_bit_cast(unsigned, __builtin_convertvector(v, bf16v2_t)); }
; __device__ __forceinline__ int tidx() { int t = threadIdx.x; asm volatile("" : "+v"(t)); return t; }
; __device__ __forceinline__ float shx(float v, int mask, int lane) { return __int_as_float(__builtin_amdgcn_ds_bpermute((lane ^ mask) << 2, __float_as_int(v))); }
; __device__ __forceinline__ size_t pidx(int row, int col) { return (size_t)(col >> 7) * ((size_t)T * 128) + (size_t)row * 128 + (col & 127); }
; __device__ __forceinline__ float bflo(unsigned u) { return __uint_as_float(u << 16); }
; __device__ __forceinline__ float bfhi(unsigned u) { return __uint_as_float(u & 0xffff0000u); }
; __device__ __forceinline__ void stage_rows128_norm(bf16_t* dst, const bf16_t* P, int r0, int rstride, int col, const float* __restrict__ gain, float qs) {
;     const int tid = tidx(), lane = tid & 63;
;     const f32x4 g0 = *(const f32x4*)(gain + (tid & 15) * 8), g1 = *(const f32x4*)(gain + (tid & 15) * 8 + 4);
; #pragma unroll
;     for (int i = 0; i < 4; ++i) {
;         const int idx = tid + 512 * i, r = idx >> 4, ch = idx & 15;
;         const u32x4 raw = *(const u32x4*)(P + pidx(r0 + r * rstride, col + ch * 8));
;         float v[8] = {bflo(raw[0]), bfhi(raw[0]), bflo(raw[1]), bfhi(raw[1]), bflo(raw[2]), bfhi(raw[2]), bflo(raw[3]), bfhi(raw[3])};
;         float ss = 0.f;
; #pragma unroll
;         for (int j = 0; j < 8; ++j) ss += v[j] * v[j];
;         ss += shx(ss, 1, lane); ss += shx(ss, 2, lane); ss += shx(ss, 4, lane); ss += shx(ss, 8, lane);
;         const float inv = rsqrtf(ss * (1.f / 128.f) + EPS) * qs;
;         u32x4 o = {pk2(v[0] * inv * g0[0], v[1] * inv * g0[1]), pk2(v[2] * inv * g0[2], v[3] * inv * g0[3]),
;                    pk2(v[4] * inv * g1[0], v[5] * inv * g1[1]), pk2(v[6] * inv * g1[2], v[7] * inv * g1[3])};
;         *(u32x4*)(dst + r * 136 + ch * 8) = o;
;     }
; }
	v_add_f32_e32 v34, v34, v35
	v_fmamk_f32 v34, v34, 0x3c000000, v184
	v_mul_f32_e32 v35, 0x4b800000, v34
	v_cmp_gt_f32_e32 vcc, s90, v34
	s_nop 1
	v_cndmask_b32_e32 v34, v34, v35, vcc
	v_rsq_f32_e32 v34, v34
	s_nop 0
	v_mul_f32_e32 v35, 0x45800000, v34
	v_cndmask_b32_e32 v34, v34, v35, vcc
	v_mul_f32_e32 v34, 0x3db504f3, v34
	v_pk_mul_f32 v[64:65], v[34:35], v[68:69] op_sel_hi:[0,1]
	v_pk_mul_f32 v[36:37], v[34:35], v[36:37] op_sel_hi:[0,1]
	v_pk_mul_f32 v[62:63], v[34:35], v[62:63] op_sel_hi:[0,1]
	v_pk_mul_f32 v[34:35], v[34:35], v[58:59] op_sel_hi:[0,1]
	v_pk_mul_f32 v[58:59], v[22:23], v[64:65]
	v_pk_mul_f32 v[36:37], v[24:25], v[36:37]
	v_pk_mul_f32 v[62:63], v[18:19], v[62:63]
	v_pk_mul_f32 v[64:65], v[20:21], v[34:35]
	v_cvt_pk_bf16_f32 v34, v58, v59
	v_cvt_pk_bf16_f32 v35, v36, v37
	v_cvt_pk_bf16_f32 v36, v62, v63
	v_cvt_pk_bf16_f32 v37, v64, v65
	v_mad_u64_u32 v[58:59], s[0:1], v70, s5, v[40:41]
	ds_write_b128 v58, v[34:37]
	v_add_u32_e32 v34, 0x200, v60
	v_ashrrev_i32_e32 v73, 4, v34
	v_add_u32_e32 v34, s4, v73
	v_ashrrev_i32_e32 v35, 31, v34
	v_lshlrev_b64 v[34:35], 8, v[34:35]
	v_lshl_add_u64 v[34:35], v[50:51], 0, v[34:35]
	v_mov_b64_e32 v[34:35], v[156:157]
	v_mov_b64_e32 v[36:37], v[158:159]
	s_waitcnt lgkmcnt(0)
	v_lshlrev_b32_e32 v64, 16, v34
	v_and_b32_e32 v65, 0xffff0000, v34
	v_lshlrev_b32_e32 v58, 16, v37
	v_and_b32_e32 v59, 0xffff0000, v37
	v_lshlrev_b32_e32 v62, 16, v36
	v_and_b32_e32 v63, 0xffff0000, v36
	v_lshlrev_b32_e32 v36, 16, v35
	v_and_b32_e32 v37, 0xffff0000, v35
	v_pk_mul_f32 v[70:71], v[64:65], v[64:65]
	v_pk_mul_f32 v[68:69], v[36:37], v[36:37]
	v_add_f32_e32 v70, v70, v71
	v_add_f32_e32 v68, v68, v70
	v_pk_mul_f32 v[66:67], v[62:63], v[62:63]
	v_add_f32_e32 v68, v69, v68
	v_add_f32_e32 v66, v66, v68
	v_pk_mul_f32 v[34:35], v[58:59], v[58:59]
	v_add_f32_e32 v66, v67, v66
	v_add_f32_e32 v34, v34, v66
	v_add_f32_e32 v34, v35, v34
	s_nop 1
	v_mov_b32_dpp v35, v34 quad_perm:[1,0,3,2] row_mask:0xf bank_mask:0xf
	s_waitcnt lgkmcnt(0)
	v_add_f32_e32 v34, v34, v35
	s_nop 1
	v_mov_b32_dpp v35, v34 quad_perm:[2,3,0,1] row_mask:0xf bank_mask:0xf
	s_waitcnt lgkmcnt(0)
	v_add_f32_e32 v34, v34, v35
	s_nop 1
	v_mov_b32_dpp v35, v34 row_shl:4 row_mask:0xf bank_mask:0x5
	v_mov_b32_dpp v35, v34 row_shr:4 row_mask:0xf bank_mask:0xa
	s_waitcnt lgkmcnt(0)
	v_add_f32_e32 v66, v34, v35
	s_nop 1
	v_mov_b32_dpp v67, v66 row_shl:8 row_mask:0xf bank_mask:0x3
	v_mov_b32_dpp v67, v66 row_shr:8 row_mask:0xf bank_mask:0xc
	v_add_u32_e32 v34, 0x400, v60
	v_ashrrev_i32_e32 v78, 4, v34
	v_add_u32_e32 v34, s4, v78
	v_ashrrev_i32_e32 v35, 31, v34
	s_waitcnt lgkmcnt(0)
	v_add_f32_e32 v66, v66, v67
	v_fmamk_f32 v66, v66, 0x3c000000, v184
	v_mul_f32_e32 v67, 0x4b800000, v66
	v_cmp_gt_f32_e32 vcc, s90, v66
	v_lshlrev_b64 v[34:35], 8, v[34:35]
	v_lshl_add_u64 v[68:69], v[50:51], 0, v[34:35]
	v_cndmask_b32_e32 v66, v66, v67, vcc
	v_rsq_f32_e32 v70, v66
	v_mad_u64_u32 v[66:67], s[0:1], v73, s5, v[40:41]
	s_movk_i32 s0, 0x88
	v_mul_f32_e32 v34, 0x45800000, v70
	v_cndmask_b32_e32 v34, v70, v34, vcc
	v_mul_f32_e32 v34, 0x3db504f3, v34
	v_pk_mul_f32 v[64:65], v[34:35], v[64:65] op_sel_hi:[0,1]
	v_pk_mul_f32 v[36:37], v[34:35], v[36:37] op_sel_hi:[0,1]
	v_pk_mul_f32 v[62:63], v[34:35], v[62:63] op_sel_hi:[0,1]
	v_pk_mul_f32 v[34:35], v[34:35], v[58:59] op_sel_hi:[0,1]
	v_pk_mul_f32 v[58:59], v[22:23], v[64:65]
	v_pk_mul_f32 v[36:37], v[24:25], v[36:37]
	v_pk_mul_f32 v[62:63], v[18:19], v[62:63]
	v_pk_mul_f32 v[64:65], v[20:21], v[34:35]
	v_cvt_pk_bf16_f32 v34, v58, v59
	v_cvt_pk_bf16_f32 v35, v36, v37
	v_cvt_pk_bf16_f32 v36, v62, v63
	v_cvt_pk_bf16_f32 v37, v64, v65
	ds_write_b128 v66, v[34:37]
	v_mov_b64_e32 v[34:35], v[160:161]
	v_mov_b64_e32 v[36:37], v[162:163]
	v_and_b32_e32 v63, 0x1ffffff8, v72
	v_and_b32_e32 v65, 0x1ffffff8, v61
	v_mul_lo_u32 v97, v53, s0
	v_mul_lo_u32 v103, v54, s0
	v_add_u32_e32 v62, s4, v53
	v_add_u32_e32 v64, s4, v54
	v_mul_lo_u32 v102, v63, s18
	v_ashrrev_i32_e32 v63, 31, v62
	v_mul_lo_u32 v104, v65, s18
	v_ashrrev_i32_e32 v65, 31, v64
	v_lshlrev_b64 v[62:63], 8, v[62:63]
	v_lshlrev_b64 v[64:65], 8, v[64:65]
	v_lshl_add_u64 v[62:63], v[38:39], 0, v[62:63]
	v_lshl_add_u64 v[38:39], v[38:39], 0, v[64:65]
	v_lshl_add_u32 v94, v102, 1, v86
	v_lshl_add_u32 v95, v97, 1, v92
	v_lshl_add_u32 v92, v103, 1, v92
	v_lshl_add_u32 v86, v104, 1, v86
	v_ashrrev_i32_e32 v59, 6, v52
	v_and_b32_e32 v58, 15, v52
	v_mul_u32_u24_e32 v112, 0x90, v58
	v_mul_u32_u24_e32 v113, 0x110, v58
	s_waitcnt lgkmcnt(0)
	v_lshlrev_b32_e32 v70, 16, v34
	v_and_b32_e32 v71, 0xffff0000, v34
	v_lshlrev_b32_e32 v66, 16, v37
	v_and_b32_e32 v67, 0xffff0000, v37
	v_lshlrev_b32_e32 v68, 16, v36
	v_and_b32_e32 v69, 0xffff0000, v36
	v_lshlrev_b32_e32 v36, 16, v35
	v_and_b32_e32 v37, 0xffff0000, v35
	v_pk_mul_f32 v[76:77], v[70:71], v[70:71]
	v_pk_mul_f32 v[74:75], v[36:37], v[36:37]
	v_add_f32_e32 v0, v76, v77
	v_add_f32_e32 v0, v74, v0
	v_pk_mul_f32 v[72:73], v[68:69], v[68:69]
	v_add_f32_e32 v0, v75, v0
	v_add_f32_e32 v0, v72, v0
	v_pk_mul_f32 v[34:35], v[66:67], v[66:67]
	v_add_f32_e32 v0, v73, v0
	v_add_f32_e32 v0, v34, v0
	v_add_f32_e32 v0, v35, v0
	s_nop 1
	v_mov_b32_dpp v61, v0 quad_perm:[1,0,3,2] row_mask:0xf bank_mask:0xf
	v_add_u32_e32 v34, 0x600, v60
	v_lshlrev_b32_e32 v74, 16, v30
	v_and_b32_e32 v75, 0xffff0000, v30
	v_ashrrev_i32_e32 v93, 4, v34
	s_waitcnt lgkmcnt(0)
	v_add_f32_e32 v0, v0, v61
	s_nop 1
	v_mov_b32_dpp v72, v0 quad_perm:[2,3,0,1] row_mask:0xf bank_mask:0xf
	v_mad_u64_u32 v[60:61], s[0:1], v78, s5, v[40:41]
	v_add_u32_e32 v34, s4, v93
	v_lshlrev_b32_e32 v78, 16, v28
	s_waitcnt lgkmcnt(0)
; __device__ __forceinline__ int tidx() { int t = threadIdx.x; asm volatile("" : "+v"(t)); return t; }
; __device__ __forceinline__ void stage_rows128_norm(bf16_t* dst, const bf16_t* P, int r0, int rstride, int col, const float* __restrict__ gain, float qs) {
;     const int tid = tidx(), lane = tid & 63;
;     const f32x4 g0 = *(const f32x4*)(gain + (tid & 15) * 8), g1 = *(const f32x4*)(gain + (tid & 15) * 8 + 4);
; #pragma unroll
;     for (int i = 0; i < 4; ++i) {
;         const int idx = tid + 512 * i, r = idx >> 4, ch = idx & 15;
;         const u32x4 raw = *(const u32x4*)(P + pidx(r0 + r * rstride, col + ch * 8));
;         float v[8] = {bflo(raw[0]), bfhi(raw[0]), bflo(raw[1]), bfhi(raw[1]), bflo(raw[2]), bfhi(raw[2]), bflo(raw[3]), bfhi(raw[3])};
;         float ss = 0.f;
; #pragma unroll
;         for (int j = 0; j < 8; ++j) ss += v[j] * v[j];
;         ss += shx(ss, 1, lane); ss += shx(ss, 2, lane); ss += shx(ss, 4, lane); ss += shx(ss, 8, lane);
;         const float inv = rsqrtf(ss * (1.f / 128.f) + EPS) * qs;
;         u32x4 o = {pk2(v[0] * inv * g0[0], v[1] * inv * g0[1]), pk2(v[2] * inv * g0[2], v[3] * inv * g0[3]),
;                    pk2(v[4] * inv * g1[0], v[5] * inv * g1[1]), pk2(v[6] * inv * g1[2], v[7] * inv * g1[3])};
;         *(u32x4*)(dst + r * 136 + ch * 8) = o;
;     }
; }
; __device__ __forceinline__ void tile_write(const TileRegs& t, unsigned char* buf, const f32x4& g0, const f32x4& g1, int tid, int lane) {
;     bf16_t* Ks = (bf16_t*)buf; bf16_t* VT = (bf16_t*)(buf + AT_VOFF);
; #pragma unroll
;     for (int i = 0; i < 2; ++i) {
;         const int idx = tid + 512 * i, r = idx >> 4, ch = idx & 15;
;         const u32x4 raw = t.k[i];
;         float v[8] = {bflo(raw[0]), bfhi(raw[0]), bflo(raw[1]), bfhi(raw[1]), bflo(raw[2]), bfhi(raw[2]), bflo(raw[3]), bfhi(raw[3])};
;         float ss = 0.f;
; #pragma unroll
;         for (int j = 0; j < 8; ++j) ss += v[j] * v[j];
;         ss += shx(ss, 1, lane); ss += shx(ss, 2, lane); ss += shx(ss, 4, lane); ss += shx(ss, 8, lane);
;         const float inv = rsqrtf(ss * (1.f / 128.f) + EPS);
;         u32x4 o = {pk2(v[0] * inv * g0[0], v[1] * inv * g0[1]), pk2(v[2] * inv * g0[2], v[3] * inv * g0[3]),
;                    pk2(v[4] * inv * g1[0], v[5] * inv * g1[1]), pk2(v[6] * inv * g1[2], v[7] * inv * g1[3])};
;         *(u32x4*)(Ks + r * 136 + ch * 8) = o;
	v_add_f32_e32 v0, v0, v72
	s_nop 1
	v_mov_b32_dpp v61, v0 row_shl:4 row_mask:0xf bank_mask:0x5
	v_mov_b32_dpp v61, v0 row_shr:4 row_mask:0xf bank_mask:0xa
	v_ashrrev_i32_e32 v35, 31, v34
	v_lshlrev_b64 v[34:35], 8, v[34:35]
	v_lshl_add_u64 v[34:35], v[50:51], 0, v[34:35]
	v_lshlrev_b32_e32 v50, 16, v33
	s_waitcnt lgkmcnt(0)
	v_add_f32_e32 v0, v0, v61
	s_nop 1
	v_mov_b32_dpp v61, v0 row_shl:8 row_mask:0xf bank_mask:0x3
	v_mov_b32_dpp v61, v0 row_shr:8 row_mask:0xf bank_mask:0xc
	v_and_b32_e32 v51, 0xffff0000, v33
	v_lshlrev_b32_e32 v72, 16, v32
	v_and_b32_e32 v73, 0xffff0000, v32
	v_lshlrev_b32_e32 v32, 16, v31
	s_waitcnt lgkmcnt(0)
	v_add_f32_e32 v0, v0, v61
	v_fmamk_f32 v0, v0, 0x3c000000, v184
	v_mul_f32_e32 v30, 0x4b800000, v0
	v_cmp_gt_f32_e32 vcc, s90, v0
	v_and_b32_e32 v33, 0xffff0000, v31
	v_lshlrev_b32_e32 v76, 16, v29
	v_cndmask_b32_e32 v0, v0, v30, vcc
	v_rsq_f32_e32 v0, v0
	v_and_b32_e32 v77, 0xffff0000, v29
	v_mov_b32_e32 v85, v75
	v_mov_b32_e32 v83, v74
	v_mul_f32_e32 v28, 0x45800000, v0
	v_cndmask_b32_e32 v0, v0, v28, vcc
	v_mul_f32_e32 v0, 0x3db504f3, v0
	v_pk_mul_f32 v[28:29], v[0:1], v[70:71] op_sel_hi:[0,1]
	v_pk_mul_f32 v[30:31], v[0:1], v[36:37] op_sel_hi:[0,1]
	v_pk_mul_f32 v[36:37], v[0:1], v[68:69] op_sel_hi:[0,1]
	v_pk_mul_f32 v[66:67], v[0:1], v[66:67] op_sel_hi:[0,1]
	v_pk_mul_f32 v[28:29], v[22:23], v[28:29]
	v_pk_mul_f32 v[30:31], v[24:25], v[30:31]
	v_pk_mul_f32 v[36:37], v[18:19], v[36:37]
	v_pk_mul_f32 v[66:67], v[20:21], v[66:67]
	v_cvt_pk_bf16_f32 v28, v28, v29
	v_cvt_pk_bf16_f32 v29, v30, v31
	v_cvt_pk_bf16_f32 v30, v36, v37
	v_cvt_pk_bf16_f32 v31, v66, v67
	ds_write_b128 v60, v[28:31]
	v_mov_b64_e32 v[28:29], v[164:165]
	v_mov_b64_e32 v[30:31], v[166:167]
	v_and_b32_e32 v37, 0xffff0000, v26
	v_lshlrev_b32_e32 v34, 16, v27
	v_and_b32_e32 v35, 0xffff0000, v27
	v_lshlrev_b32_e32 v36, 16, v26
	v_mov_b32_e32 v84, v37
	v_pk_mul_f32 v[26:27], v[50:51], v[50:51]
	v_pk_mul_f32 v[60:61], v[72:73], v[72:73]
	v_pk_mul_f32 v[66:67], v[32:33], v[32:33]
	v_pk_mul_f32 v[68:69], v[76:77], v[76:77]
	v_pk_mul_f32 v[70:71], v[78:79], v[78:79]
	v_pk_mul_f32 v[80:81], v[34:35], v[34:35]
	v_mov_b32_e32 v82, v36
	v_pk_mul_f32 v[84:85], v[84:85], v[84:85]
	v_mov_b32_e32 v88, v80
	v_mov_b32_e32 v89, v66
	v_mov_b32_e32 v66, v81
	v_mov_b32_e32 v80, v70
	v_mov_b32_e32 v81, v60
	v_mov_b32_e32 v60, v71
	v_mov_b32_e32 v70, v68
	v_mov_b32_e32 v71, v26
	v_mov_b32_e32 v26, v69
	v_pk_fma_f32 v[68:69], v[82:83], v[82:83], v[84:85]
	v_lshlrev_b32_e32 v0, 8, v91
	v_pk_add_f32 v[68:69], v[88:89], v[68:69]
	s_waitcnt lgkmcnt(0)
	v_lshlrev_b32_e32 v82, 16, v28
	v_pk_add_f32 v[66:67], v[66:67], v[68:69]
	v_and_b32_e32 v83, 0xffff0000, v28
	v_pk_add_f32 v[66:67], v[80:81], v[66:67]
	v_lshlrev_b32_e32 v80, 16, v29
	v_pk_add_f32 v[60:61], v[60:61], v[66:67]
	v_lshl_add_u64 v[66:67], s[2:3], 0, v[0:1]
	v_pk_add_f32 v[60:61], v[70:71], v[60:61]
	v_lshl_add_u64 v[64:65], v[66:67], 0, v[42:43]
	v_pk_add_f32 v[26:27], v[26:27], v[60:61]
	s_nop 1
	v_mov_b32_dpp v61, v27 quad_perm:[1,0,3,2] row_mask:0xf bank_mask:0xf
	s_nop 1
	v_mov_b32_dpp v60, v26 quad_perm:[1,0,3,2] row_mask:0xf bank_mask:0xf
	v_and_b32_e32 v81, 0xffff0000, v29
	v_pk_mul_f32 v[88:89], v[82:83], v[82:83]
	v_lshl_add_u64 v[64:65], v[64:65], 0, v[44:45]
	v_pk_mul_f32 v[84:85], v[80:81], v[80:81]
	s_waitcnt lgkmcnt(0)
	v_pk_add_f32 v[26:27], v[26:27], v[60:61]
	s_nop 1
	v_mov_b32_dpp v61, v27 quad_perm:[2,3,0,1] row_mask:0xf bank_mask:0xf
	s_nop 1
	v_mov_b32_dpp v60, v26 quad_perm:[2,3,0,1] row_mask:0xf bank_mask:0xf
	v_lshl_add_u64 v[66:67], v[66:67], 0, v[46:47]
	v_lshl_add_u64 v[66:67], v[66:67], 0, v[48:49]
	s_waitcnt lgkmcnt(0)
	v_pk_add_f32 v[26:27], v[26:27], v[60:61]
	s_nop 1
	v_mov_b32_dpp v61, v27 row_shl:4 row_mask:0xf bank_mask:0x5
	v_mov_b32_dpp v61, v27 row_shr:4 row_mask:0xf bank_mask:0xa
	s_nop 1
	v_mov_b32_dpp v60, v26 row_shl:4 row_mask:0xf bank_mask:0x5
	v_mov_b32_dpp v60, v26 row_shr:4 row_mask:0xf bank_mask:0xa
	s_waitcnt lgkmcnt(0)
	v_pk_add_f32 v[26:27], v[26:27], v[60:61]
	s_nop 1
	v_mov_b32_dpp v61, v27 row_shl:8 row_mask:0xf bank_mask:0x3
	v_mov_b32_dpp v61, v27 row_shr:8 row_mask:0xf bank_mask:0xc
	s_nop 1
	v_mov_b32_dpp v60, v26 row_shl:8 row_mask:0xf bank_mask:0x3
	v_mov_b32_dpp v60, v26 row_shr:8 row_mask:0xf bank_mask:0xc
	s_waitcnt lgkmcnt(0)
	v_pk_add_f32 v[26:27], v[26:27], v[60:61]
	s_nop 0
	v_pk_fma_f32 v[26:27], v[26:27], s[76:77], v[184:185] op_sel_hi:[1,0,0]
	v_mad_u64_u32 v[60:61], s[18:19], v93, s5, v[40:41]
	v_mul_f32_e32 v0, 0x4b800000, v27
	v_cmp_gt_f32_e32 vcc, s90, v27
	v_mul_f32_e32 v45, 0x4b800000, v26
	v_cmp_gt_f32_e64 s[0:1], s90, v26
	v_cndmask_b32_e32 v0, v27, v0, vcc
	v_rsq_f32_e32 v0, v0
	v_cndmask_b32_e64 v26, v26, v45, s[0:1]
	v_rsq_f32_e32 v26, v26
	s_mov_b32 s18, 0
	v_mul_f32_e32 v27, 0x45800000, v0
	v_cndmask_b32_e32 v0, v0, v27, vcc
	v_pk_mul_f32 v[68:69], v[0:1], v[74:75] op_sel_hi:[0,1]
	v_pk_mul_f32 v[32:33], v[0:1], v[32:33] op_sel_hi:[0,1]
	v_pk_mul_f32 v[70:71], v[0:1], v[72:73] op_sel_hi:[0,1]
	v_pk_mul_f32 v[50:51], v[0:1], v[50:51] op_sel_hi:[0,1]
	v_add_f32_e32 v0, v88, v89
	v_lshlrev_b32_e32 v74, 16, v30
	v_and_b32_e32 v75, 0xffff0000, v30
	v_add_f32_e32 v0, v84, v0
	v_lshlrev_b32_e32 v72, 16, v31
	v_and_b32_e32 v73, 0xffff0000, v31
	v_pk_mul_f32 v[30:31], v[74:75], v[74:75]
	v_add_f32_e32 v0, v85, v0
	v_add_f32_e32 v0, v30, v0
	v_pk_mul_f32 v[28:29], v[72:73], v[72:73]
	v_add_f32_e32 v0, v31, v0
	v_add_f32_e32 v0, v28, v0
	v_mul_f32_e32 v40, 0x45800000, v26
	v_add_f32_e32 v0, v29, v0
	v_cndmask_b32_e64 v26, v26, v40, s[0:1]
	s_nop 1
	v_mov_b32_dpp v40, v0 quad_perm:[1,0,3,2] row_mask:0xf bank_mask:0xf
	v_pk_mul_f32 v[30:31], v[26:27], v[78:79] op_sel_hi:[0,1]
	v_pk_mul_f32 v[28:29], v[26:27], v[34:35] op_sel_hi:[0,1]
	v_pk_mul_f32 v[34:35], v[6:7], v[68:69]
	v_pk_mul_f32 v[68:69], v[2:3], v[30:31]
	s_waitcnt lgkmcnt(0)
; __device__ __forceinline__ unsigned pk2(float lo, float hi) { const f32v2_t v = {lo, hi}; return __builtin_bit_cast(unsigned, __builtin_convertvector(v, bf16v2_t)); }
; __device__ __forceinline__ float shx(float v, int mask, int lane) { return __int_as_float(__builtin_amdgcn_ds_bpermute((lane ^ mask) << 2, __float_as_int(v))); }
; __device__ __forceinline__ float bflo(unsigned u) { return __uint_as_float(u << 16); }
; __device__ __forceinline__ void tile_write(const TileRegs& t, unsigned char* buf, const f32x4& g0, const f32x4& g1, int tid, int lane) {
;     bf16_t* Ks = (bf16_t*)buf; bf16_t* VT = (bf16_t*)(buf + AT_VOFF);
; #pragma unroll
;     for (int i = 0; i < 2; ++i) {
;         const int idx = tid + 512 * i, r = idx >> 4, ch = idx & 15;
;         const u32x4 raw = t.k[i];
;         float v[8] = {bflo(raw[0]), bfhi(raw[0]), bflo(raw[1]), bfhi(raw[1]), bflo(raw[2]), bfhi(raw[2]), bflo(raw[3]), bfhi(raw[3])};
;         float ss = 0.f;
; #pragma unroll
;         for (int j = 0; j < 8; ++j) ss += v[j] * v[j];
;         ss += shx(ss, 1, lane); ss += shx(ss, 2, lane); ss += shx(ss, 4, lane); ss += shx(ss, 8, lane);
;         const float inv = rsqrtf(ss * (1.f / 128.f) + EPS);
;         u32x4 o = {pk2(v[0] * inv * g0[0], v[1] * inv * g0[1]), pk2(v[2] * inv * g0[2], v[3] * inv * g0[3]),
;                    pk2(v[4] * inv * g1[0], v[5] * inv * g1[1]), pk2(v[6] * inv * g1[2], v[7] * inv * g1[3])};
;         *(u32x4*)(Ks + r * 136 + ch * 8) = o;
;         const u32x4 rv = t.v[i];
;         bf16_t* d = VT + ((idx >> 6) * 8) * 72 + (idx & 63);
;         d[0] = (bf16_t)(rv[0] & 0xffff); d[72] = (bf16_t)(rv[0] >> 16); d[144] = (bf16_t)(rv[1] & 0xffff); d[216] = (bf16_t)(rv[1] >> 16);
;         d[288] = (bf16_t)(rv[2] & 0xffff); d[360] = (bf16_t)(rv[2] >> 16); d[432] = (bf16_t)(rv[3] & 0xffff); d[504] = (bf16_t)(rv[3] >> 16);
;     }
; }
; __device__ __forceinline__ void sb_item(const Params& p, int item, int l, unsigned char* lds) {
;     ...
;     tile_write(tr, lds + AT_BUF, gk0, gk1, tid, lane);
;     tile_load(tr, P, 64 * (J - 1), 1, kcol, vcol, tid);
;     __syncthreads();
;     bf16x8 qf[4];
; #pragma unroll
;     for (int ks = 0; ks < 4; ++ks) qf[ks] = *(const bf16x8*)(Qs + (16 * w + fr) * 136 + 32 * ks + 8 * fq);
;     f32x4 oacc[8];
; #pragma unroll
;     for (int db = 0; db < 8; ++db) oacc[db] = (f32x4){0.f, 0.f, 0.f, 0.f};
	v_add_f32_e32 v0, v0, v40
	s_nop 1
	v_mov_b32_dpp v45, v0 quad_perm:[2,3,0,1] row_mask:0xf bank_mask:0xf
	v_pk_mul_f32 v[36:37], v[26:27], v[36:37] op_sel_hi:[0,1]
	v_pk_mul_f32 v[26:27], v[26:27], v[76:77] op_sel_hi:[0,1]
	v_pk_mul_f32 v[40:41], v[2:3], v[70:71]
	v_pk_mul_f32 v[70:71], v[4:5], v[26:27]
	s_waitcnt lgkmcnt(0)
	v_add_f32_e32 v0, v0, v45
	s_nop 1
	v_mov_b32_dpp v45, v0 row_shl:4 row_mask:0xf bank_mask:0x5
	v_mov_b32_dpp v45, v0 row_shr:4 row_mask:0xf bank_mask:0xa
	v_cvt_pk_bf16_f32 v26, v34, v35
	v_pk_mul_f32 v[50:51], v[4:5], v[50:51]
	v_pk_mul_f32 v[36:37], v[6:7], v[36:37]
	v_pk_mul_f32 v[56:57], v[8:9], v[28:29]
	s_waitcnt lgkmcnt(0)
	v_add_f32_e32 v0, v0, v45
	s_nop 1
	v_mov_b32_dpp v31, v0 row_shl:8 row_mask:0xf bank_mask:0x3
	v_mov_b32_dpp v31, v0 row_shr:8 row_mask:0xf bank_mask:0xc
	v_cvt_pk_bf16_f32 v28, v40, v41
	v_cvt_pk_bf16_f32 v29, v50, v51
	v_cvt_pk_bf16_f32 v30, v36, v37
	v_pk_mul_f32 v[32:33], v[8:9], v[32:33]
	s_waitcnt lgkmcnt(0)
	v_add_f32_e32 v0, v0, v31
	v_fmamk_f32 v0, v0, 0x3c000000, v184
	v_mul_f32_e32 v31, 0x4b800000, v0
	v_cmp_gt_f32_e32 vcc, s90, v0
	v_cvt_pk_bf16_f32 v27, v32, v33
	v_cvt_pk_bf16_f32 v32, v68, v69
	v_cndmask_b32_e32 v0, v0, v31, vcc
	v_rsq_f32_e32 v0, v0
	v_cvt_pk_bf16_f32 v31, v56, v57
	v_cvt_pk_bf16_f32 v33, v70, v71
	v_readlane_b32 s0, v246, 59
	v_mul_f32_e32 v34, 0x45800000, v0
	v_cndmask_b32_e32 v0, v0, v34, vcc
	v_mul_f32_e32 v0, 0x3db504f3, v0
	v_pk_mul_f32 v[34:35], v[0:1], v[82:83] op_sel_hi:[0,1]
	v_pk_mul_f32 v[36:37], v[0:1], v[80:81] op_sel_hi:[0,1]
	v_pk_mul_f32 v[40:41], v[0:1], v[74:75] op_sel_hi:[0,1]
	v_pk_mul_f32 v[50:51], v[0:1], v[72:73] op_sel_hi:[0,1]
	v_pk_mul_f32 v[22:23], v[22:23], v[34:35]
	v_pk_mul_f32 v[24:25], v[24:25], v[36:37]
	v_pk_mul_f32 v[34:35], v[18:19], v[40:41]
	v_pk_mul_f32 v[36:37], v[20:21], v[50:51]
	v_cvt_pk_bf16_f32 v18, v22, v23
	v_cvt_pk_bf16_f32 v19, v24, v25
	v_cvt_pk_bf16_f32 v20, v34, v35
	v_cvt_pk_bf16_f32 v21, v36, v37
	ds_write_b128 v60, v[18:21]
	ds_write_b128 v95, v[26:29] offset:34816
	ds_write_b16 v94, v14 offset:52224
	ds_write_b16_d16_hi v94, v14 offset:52368
	ds_write_b16 v94, v15 offset:52512
	ds_write_b16_d16_hi v94, v15 offset:52656
	ds_write_b16 v94, v16 offset:52800
	ds_write_b16_d16_hi v94, v16 offset:52944
	ds_write_b16 v94, v17 offset:53088
	ds_write_b16_d16_hi v94, v17 offset:53232
	ds_write_b128 v92, v[30:33] offset:34816
	ds_write_b16 v86, v10 offset:52224
	ds_write_b16_d16_hi v86, v10 offset:52368
	ds_write_b16 v86, v11 offset:52512
	ds_write_b16_d16_hi v86, v11 offset:52656
	ds_write_b16 v86, v12 offset:52800
	ds_write_b16_d16_hi v86, v12 offset:52944
	ds_write_b16 v86, v13 offset:53088
	ds_write_b16_d16_hi v86, v13 offset:53232
	flat_load_dwordx4 v[10:13], v[62:63]
	flat_load_dwordx4 v[14:17], v[64:65]
	flat_load_dwordx4 v[18:21], v[38:39]
	flat_load_dwordx4 v[30:33], v[66:67]
	v_add_u32_e32 v50, s17, v54
	v_lshlrev_b32_e32 v0, 4, v59
	v_lshl_add_u32 v107, v59, 2, s0
	s_add_u32 s0, s44, 0x17214000
	v_ashrrev_i32_e32 v51, 31, v50
	v_or_b32_e32 v22, v0, v58
	s_addc_u32 s1, s45, 0
	v_lshlrev_b64 v[50:51], 8, v[50:51]
	v_mul_lo_u32 v22, v22, s5
	v_lshl_add_u64 v[88:89], s[0:1], 0, v[50:51]
	v_add_u32_e32 v50, s17, v53
	v_add3_u32 v38, 0, v22, v105
	v_ashrrev_i32_e32 v51, 31, v50
	s_waitcnt lgkmcnt(0)
	s_barrier
	ds_read_b128 v[22:25], v38
	ds_read_b128 v[26:29], v38 offset:64
	ds_read_b128 v[34:37], v38 offset:128
	ds_read_b128 v[38:41], v38 offset:192
	v_bfe_u32 v45, v52, 4, 2
	v_add_u32_e32 v0, s4, v0
	v_lshlrev_b64 v[50:51], 8, v[50:51]
	v_or_b32_e32 v86, v0, v58
	v_or_b32_e32 v106, 15, v0
	v_lshlrev_b32_e32 v0, 2, v45
	v_cmp_ne_u32_e64 s[40:41], 1, v45
	v_cmp_eq_u32_e64 s[42:43], 2, v45
	v_lshlrev_b32_e32 v111, 3, v45
	v_lshlrev_b32_e32 v45, 4, v58
	v_lshl_add_u64 v[90:91], s[0:1], 0, v[50:51]
	v_or_b32_e32 v88, v88, v45
	v_or_b32_e32 v90, v90, v45
	v_or_b32_e32 v45, s17, v87
	v_lshlrev_b32_e32 v45, 8, v45
	s_mov_b64 s[0:1], 0x17214000
	v_or3_b32 v42, v42, v45, v44
	v_or3_b32 v46, v46, v45, v48
	v_lshl_add_u64 v[94:95], v[42:43], 0, s[0:1]
	v_mov_b32_e32 v42, 0
	v_lshl_add_u64 v[92:93], v[46:47], 0, s[0:1]
	v_mov_b32_e32 v43, v42
	v_mov_b32_e32 v44, v42
	v_mov_b32_e32 v45, v42
	v_mov_b32_e32 v58, v42
	v_mov_b32_e32 v59, v42
	v_mov_b32_e32 v60, v42
	v_mov_b32_e32 v61, v42
	v_mov_b32_e32 v54, v42
	v_mov_b32_e32 v55, v42
	v_mov_b32_e32 v56, v42
	v_mov_b32_e32 v57, v42
	v_mov_b32_e32 v50, v42
	v_mov_b32_e32 v51, v42
	v_mov_b32_e32 v52, v42
	v_mov_b32_e32 v53, v42
	v_mov_b32_e32 v70, v42
	v_mov_b32_e32 v71, v42
	v_mov_b32_e32 v72, v42
	v_mov_b32_e32 v73, v42
	v_mov_b32_e32 v66, v42
	v_mov_b32_e32 v67, v42
	v_mov_b32_e32 v68, v42
	v_mov_b32_e32 v69, v42
	v_mov_b32_e32 v62, v42
	v_mov_b32_e32 v63, v42
	v_mov_b32_e32 v64, v42
	v_mov_b32_e32 v65, v42
	v_mov_b32_e32 v46, v42
	v_mov_b32_e32 v47, v42
	v_mov_b32_e32 v48, v42
	v_mov_b32_e32 v49, v42
	s_branch .LBB0_124

; __device__ __forceinline__ unsigned pk2(float lo, float hi) { const f32v2_t v = {lo, hi}; return __builtin_bit_cast(unsigned, __builtin_convertvector(v, bf16v2_t)); }
; __device__ __forceinline__ float shx(float v, int mask, int lane) { return __int_as_float(__builtin_amdgcn_ds_bpermute((lane ^ mask) << 2, __float_as_int(v))); }
; __device__ __forceinline__ float bflo(unsigned u) { return __uint_as_float(u << 16); }
; __device__ __forceinline__ void tile_write(const TileRegs& t, unsigned char* buf, const f32x4& g0, const f32x4& g1, int tid, int lane) {
;     bf16_t* Ks = (bf16_t*)buf; bf16_t* VT = (bf16_t*)(buf + AT_VOFF);
; #pragma unroll
;     for (int i = 0; i < 2; ++i) {
;         const int idx = tid + 512 * i, r = idx >> 4, ch = idx & 15;
;         const u32x4 raw = t.k[i];
;         float v[8] = {bflo(raw[0]), bfhi(raw[0]), bflo(raw[1]), bfhi(raw[1]), bflo(raw[2]), bfhi(raw[2]), bflo(raw[3]), bfhi(raw[3])};
;         float ss = 0.f;
; #pragma unroll
;         for (int j = 0; j < 8; ++j) ss += v[j] * v[j];
;         ss += shx(ss, 1, lane); ss += shx(ss, 2, lane); ss += shx(ss, 4, lane); ss += shx(ss, 8, lane);
;         const float inv = rsqrtf(ss * (1.f / 128.f) + EPS);
;         u32x4 o = {pk2(v[0] * inv * g0[0], v[1] * inv * g0[1]), pk2(v[2] * inv * g0[2], v[3] * inv * g0[3]),
;                    pk2(v[4] * inv * g1[0], v[5] * inv * g1[1]), pk2(v[6] * inv * g1[2], v[7] * inv * g1[3])};
;         *(u32x4*)(Ks + r * 136 + ch * 8) = o;
;         const u32x4 rv = t.v[i];
;         bf16_t* d = VT + ((idx >> 6) * 8) * 72 + (idx & 63);
;         d[0] = (bf16_t)(rv[0] & 0xffff); d[72] = (bf16_t)(rv[0] >> 16); d[144] = (bf16_t)(rv[1] & 0xffff); d[216] = (bf16_t)(rv[1] >> 16);
;         d[288] = (bf16_t)(rv[2] & 0xffff); d[360] = (bf16_t)(rv[2] >> 16); d[432] = (bf16_t)(rv[3] & 0xffff); d[504] = (bf16_t)(rv[3] >> 16);
;     }
; }
; __device__ __forceinline__ void sb_item(const Params& p, int item, int l, unsigned char* lds) {
;     ...
;         float rm = R;
; #pragma unroll
;         for (int o = 32; o > 0; o >>= 1) rm = fmaxf(rm, shx(rm, o, lane));
;         if (lane == 0) flags[cur * 8 + w] = rm;
;         if (J == 0) break;
;         tile_write(tr, lds + AT_BUF + (cur ^ 1) * AT_BUFSZ, gk0, gk1, tid, lane);
;         if (J >= 2) tile_load(tr, P, 64 * (J - 2), 1, kcol, vcol, tid);
.LBB0_158:
	s_or_b64 exec, exec, s[92:93]
	ds_bpermute_b32 v74, v109, v114
	s_waitcnt lgkmcnt(0)
	v_max_f32_e32 v75, v114, v114
	s_waitcnt lgkmcnt(0)
	v_max_f32_e32 v74, v74, v74
	v_max_f32_e32 v74, v75, v74
	ds_bpermute_b32 v75, v108, v74
	s_waitcnt lgkmcnt(0)
	v_max_f32_e32 v75, v75, v75
	v_max_f32_e32 v74, v74, v75
	s_nop 1
	v_mov_b32_dpp v75, v74 row_shl:8 row_mask:0xf bank_mask:0x3
	v_mov_b32_dpp v75, v74 row_shr:8 row_mask:0xf bank_mask:0xc
	s_waitcnt lgkmcnt(0)
	v_max_f32_e32 v75, v75, v75
	v_max_f32_e32 v74, v74, v75
	s_nop 1
	v_mov_b32_dpp v75, v74 row_shl:4 row_mask:0xf bank_mask:0x5
	v_mov_b32_dpp v75, v74 row_shr:4 row_mask:0xf bank_mask:0xa
	s_waitcnt lgkmcnt(0)
	v_max_f32_e32 v75, v75, v75
	v_max_f32_e32 v74, v74, v75
	s_nop 1
	v_mov_b32_dpp v75, v74 quad_perm:[2,3,0,1] row_mask:0xf bank_mask:0xf
	s_waitcnt lgkmcnt(0)
	v_max_f32_e32 v75, v75, v75
	v_max_f32_e32 v74, v74, v75
	s_nop 1
	v_mov_b32_dpp v75, v74 quad_perm:[1,0,3,2] row_mask:0xf bank_mask:0xf
	s_and_saveexec_b64 s[0:1], s[36:37]
	s_cbranch_execz .LBB0_160
	s_waitcnt lgkmcnt(0)
	v_max_f32_e32 v75, v75, v75
	v_max_f32_e32 v74, v74, v74
	v_max_f32_e32 v74, v74, v75
	v_lshl_add_u32 v75, s18, 5, v107
	ds_write_b32 v75, v74
.LBB0_160:
	s_or_b64 exec, exec, s[0:1]
	s_cmpk_eq_i32 s17, 0xffc0
	s_mov_b64 s[0:1], -1
	s_cbranch_scc1 .LBB0_123
	s_waitcnt vmcnt(0)
	v_and_b32_e32 v117, 0xffff0000, v10
	v_and_b32_e32 v131, 0xffff0000, v18
	v_lshlrev_b32_e32 v82, 16, v11
	v_and_b32_e32 v83, 0xffff0000, v11
	v_lshlrev_b32_e32 v116, 16, v10
	v_lshlrev_b32_e32 v126, 16, v19
	v_and_b32_e32 v127, 0xffff0000, v19
	v_lshlrev_b32_e32 v130, 16, v18
	v_mov_b32_e32 v134, v131
	v_mov_b32_e32 v135, v117
	v_pk_mul_f32 v[84:85], v[82:83], v[82:83]
	v_pk_mul_f32 v[128:129], v[126:127], v[126:127]
	v_mov_b32_e32 v132, v130
	v_mov_b32_e32 v133, v116
	v_pk_mul_f32 v[134:135], v[134:135], v[134:135]
	v_lshlrev_b32_e32 v76, 16, v12
	v_and_b32_e32 v77, 0xffff0000, v12
	v_lshlrev_b32_e32 v122, 16, v20
	v_and_b32_e32 v123, 0xffff0000, v20
	v_pk_fma_f32 v[132:133], v[132:133], v[132:133], v[134:135]
	v_mov_b32_e32 v134, v128
	v_mov_b32_e32 v135, v84
	v_pk_mul_f32 v[80:81], v[76:77], v[76:77]
	v_pk_mul_f32 v[124:125], v[122:123], v[122:123]
	v_pk_add_f32 v[132:133], v[134:135], v[132:133]
	v_mov_b32_e32 v84, v129
	v_lshlrev_b32_e32 v78, 16, v13
	v_and_b32_e32 v79, 0xffff0000, v13
	v_lshlrev_b32_e32 v118, 16, v21
	v_and_b32_e32 v119, 0xffff0000, v21
	v_pk_add_f32 v[84:85], v[84:85], v[132:133]
	v_mov_b32_e32 v128, v124
	v_mov_b32_e32 v129, v80
	s_waitcnt lgkmcnt(0)
	v_pk_mul_f32 v[74:75], v[78:79], v[78:79]
	v_pk_mul_f32 v[120:121], v[118:119], v[118:119]
	v_pk_add_f32 v[84:85], v[128:129], v[84:85]
	v_mov_b32_e32 v80, v125
	v_pk_add_f32 v[80:81], v[80:81], v[84:85]
	v_mov_b32_e32 v84, v120
	v_mov_b32_e32 v85, v74
	v_pk_add_f32 v[80:81], v[84:85], v[80:81]
	v_mov_b32_e32 v74, v121
	v_pk_add_f32 v[74:75], v[74:75], v[80:81]
	s_nop 1
	v_mov_b32_dpp v81, v75 quad_perm:[1,0,3,2] row_mask:0xf bank_mask:0xf
	s_nop 1
	v_mov_b32_dpp v80, v74 quad_perm:[1,0,3,2] row_mask:0xf bank_mask:0xf
	s_xor_b32 s4, s18, 1
	s_mul_i32 s0, s4, 0x8c00
	s_add_i32 s0, s0, 0
	v_lshl_add_u32 v85, v96, 1, s0
	s_waitcnt lgkmcnt(0)
	v_pk_add_f32 v[74:75], v[74:75], v[80:81]
	s_nop 1
	v_mov_b32_dpp v81, v75 quad_perm:[2,3,0,1] row_mask:0xf bank_mask:0xf
	s_nop 1
	v_mov_b32_dpp v80, v74 quad_perm:[2,3,0,1] row_mask:0xf bank_mask:0xf
	v_lshl_add_u32 v115, v97, 1, v85
	s_cmp_lt_i32 s16, 2
	s_waitcnt lgkmcnt(0)
	v_pk_add_f32 v[74:75], v[74:75], v[80:81]
	s_nop 1
	v_mov_b32_dpp v81, v75 row_shl:4 row_mask:0xf bank_mask:0x5
	v_mov_b32_dpp v81, v75 row_shr:4 row_mask:0xf bank_mask:0xa
	s_nop 1
	v_mov_b32_dpp v80, v74 row_shl:4 row_mask:0xf bank_mask:0x5
	v_mov_b32_dpp v80, v74 row_shr:4 row_mask:0xf bank_mask:0xa
	s_waitcnt lgkmcnt(0)
	v_pk_add_f32 v[74:75], v[74:75], v[80:81]
	s_nop 1
	v_mov_b32_dpp v81, v75 row_shl:8 row_mask:0xf bank_mask:0x3
	v_mov_b32_dpp v81, v75 row_shr:8 row_mask:0xf bank_mask:0xc
	s_nop 1
	v_mov_b32_dpp v80, v74 row_shl:8 row_mask:0xf bank_mask:0x3
	v_mov_b32_dpp v80, v74 row_shr:8 row_mask:0xf bank_mask:0xc
	s_waitcnt lgkmcnt(0)
	v_pk_add_f32 v[74:75], v[74:75], v[80:81]
	s_nop 0
	v_pk_fma_f32 v[80:81], v[74:75], s[76:77], v[184:185] op_sel_hi:[1,0,0]
	s_nop 0
	v_mul_f32_e32 v74, 0x4b800000, v81
	v_cmp_gt_f32_e32 vcc, s90, v81
	s_nop 1
	v_cndmask_b32_e32 v74, v81, v74, vcc
	v_rsq_f32_e32 v74, v74
	v_lshl_add_u32 v81, v87, 1, s0
	v_lshl_add_u32 v120, v102, 1, v81
	v_mul_f32_e32 v75, 0x45800000, v74
	v_cndmask_b32_e32 v84, v74, v75, vcc
	v_pk_mul_f32 v[74:75], v[84:85], v[116:117] op_sel_hi:[0,1]
	v_pk_mul_f32 v[82:83], v[84:85], v[82:83] op_sel_hi:[0,1]
	v_pk_mul_f32 v[76:77], v[84:85], v[76:77] op_sel_hi:[0,1]
	v_pk_mul_f32 v[78:79], v[84:85], v[78:79] op_sel_hi:[0,1]
	v_pk_mul_f32 v[74:75], v[6:7], v[74:75]
	v_pk_mul_f32 v[82:83], v[8:9], v[82:83]
	v_pk_mul_f32 v[76:77], v[2:3], v[76:77]
	v_pk_mul_f32 v[78:79], v[4:5], v[78:79]
	v_cvt_pk_bf16_f32 v74, v74, v75
	v_cvt_pk_bf16_f32 v75, v82, v83
	v_cvt_pk_bf16_f32 v76, v76, v77
	v_cvt_pk_bf16_f32 v77, v78, v79
	ds_write_b128 v115, v[74:77] offset:34816
	ds_write_b16 v120, v14 offset:52224
	ds_write_b16_d16_hi v120, v14 offset:52368
	ds_write_b16 v120, v15 offset:52512
	ds_write_b16_d16_hi v120, v15 offset:52656
	ds_write_b16 v120, v16 offset:52800
	v_mul_f32_e32 v74, 0x4b800000, v80
	v_cmp_gt_f32_e32 vcc, s90, v80
	ds_write_b16_d16_hi v120, v16 offset:52944
	ds_write_b16 v120, v17 offset:53088
	ds_write_b16_d16_hi v120, v17 offset:53232
	v_cndmask_b32_e32 v74, v80, v74, vcc
	v_rsq_f32_e32 v74, v74
	s_nop 0
	v_mul_f32_e32 v75, 0x45800000, v74
	v_cndmask_b32_e32 v78, v74, v75, vcc
	v_pk_mul_f32 v[74:75], v[78:79], v[130:131] op_sel_hi:[0,1]
	v_pk_mul_f32 v[76:77], v[78:79], v[126:127] op_sel_hi:[0,1]
	v_pk_mul_f32 v[74:75], v[6:7], v[74:75]
	v_pk_mul_f32 v[76:77], v[8:9], v[76:77]
	v_cvt_pk_bf16_f32 v74, v74, v75
	v_cvt_pk_bf16_f32 v75, v76, v77
	v_pk_mul_f32 v[76:77], v[78:79], v[122:123] op_sel_hi:[0,1]
	v_pk_mul_f32 v[78:79], v[78:79], v[118:119] op_sel_hi:[0,1]
	v_pk_mul_f32 v[76:77], v[2:3], v[76:77]
	v_pk_mul_f32 v[78:79], v[4:5], v[78:79]
	v_cvt_pk_bf16_f32 v76, v76, v77
	v_cvt_pk_bf16_f32 v77, v78, v79
	v_lshl_add_u32 v78, v103, 1, v85
	ds_write_b128 v78, v[74:77] offset:34816
	v_lshl_add_u32 v74, v104, 1, v81
	ds_write_b16 v74, v30 offset:52224
	ds_write_b16_d16_hi v74, v30 offset:52368
	ds_write_b16 v74, v31 offset:52512
	ds_write_b16_d16_hi v74, v31 offset:52656
	ds_write_b16 v74, v32 offset:52800
	ds_write_b16_d16_hi v74, v32 offset:52944
	ds_write_b16 v74, v33 offset:53088
	ds_write_b16_d16_hi v74, v33 offset:53232
	s_cbranch_scc1 .LBB0_122
	v_lshl_add_u64 v[10:11], s[26:27], 0, v[90:91]
	v_lshl_add_u64 v[14:15], s[26:27], 0, v[94:95]
	v_lshl_add_u64 v[18:19], s[26:27], 0, v[88:89]
	v_lshl_add_u64 v[30:31], s[26:27], 0, v[92:93]
	flat_load_dwordx4 v[10:13], v[10:11]
	s_nop 0
	flat_load_dwordx4 v[14:17], v[14:15]
	s_nop 0
	flat_load_dwordx4 v[18:21], v[18:19]
	s_nop 0
	flat_load_dwordx4 v[30:33], v[30:31]
	s_branch .LBB0_122

; __device__ __forceinline__ unsigned xb_ld(unsigned* p)              { return __hip_atomic_load(p, __ATOMIC_RELAXED, __HIP_MEMORY_SCOPE_AGENT); }
; __device__ __forceinline__ unsigned xb_add(unsigned* p, unsigned v) { return __hip_atomic_fetch_add(p, v, __ATOMIC_RELAXED, __HIP_MEMORY_SCOPE_AGENT); }
; #define XB_SPIN(cond, bar) do { unsigned _sp = 0; while (cond) { __builtin_amdgcn_s_sleep(1); \
;     if ((++_sp & 255u) == 0u) { if (xb_ld(&(bar)[XB_TMO])) break; if (_sp > XB_SPIN_CAP) { atomicAdd(&(bar)[XB_TMO], 1u); break; } } } } while (0)
; __device__ __forceinline__ void xcd_barrier(const XcdBarrier& b) {
;     asm volatile("s_waitcnt vmcnt(0)" ::: "memory");
;     __syncthreads();
;     if (threadIdx.x == 0) {
;         unsigned* bar = b.bar; asm volatile("" : "+s"(bar));
;         __builtin_amdgcn_s_waitcnt(0);
;         unsigned nloc = b.st[0], nx = b.st[1];
;         if (nloc == 0u) { xcd_barrier_complete(bar, b.x, nloc, nx); b.st[0] = nloc; b.st[1] = nx; }
;         const unsigned old = xb_add(&bar[XB_XSUB(b.x)], 1u);
;         const unsigned gen = old / nloc;
;         if (old + 1u == (gen + 1u) * nloc) {
;             __builtin_amdgcn_fence(__ATOMIC_RELEASE, "agent");
;             asm volatile("s_waitcnt vmcnt(0)" ::: "memory");
;             const unsigned og = xb_add(&bar[XB_TOP], 1u);
;             const unsigned tg = og / nx;
;             if (og + 1u == (tg + 1u) * nx) xb_add(&bar[XB_TOPGEN], 1u);
;             else XB_SPIN(xb_ld(&bar[XB_TOPGEN]) == tg, bar);
;             __builtin_amdgcn_fence(__ATOMIC_ACQUIRE, "agent");
;             asm volatile("s_waitcnt vmcnt(0)" ::: "memory");
;         } else {
;             XB_SPIN(xb_ld(&bar[XB_TOPGEN]) == gen, bar);
;             __builtin_amdgcn_fence(__ATOMIC_ACQUIRE, "agent");
;             asm volatile("s_waitcnt vmcnt(0)" ::: "memory");
;         }
.LBB0_822:
	v_readlane_b32 s4, v246, 51
	s_add_u32 s4, s2, s4
	s_addc_u32 s5, s3, 0
	v_mov_b32_e32 v3, s4
	v_add_co_u32_e32 v4, vcc, 0x1000, v3
	v_mov_b32_e32 v3, s5
	s_nop 0
	v_addc_co_u32_e32 v5, vcc, 0, v3, vcc
	flat_atomic_add v4, v[4:5], v210 offset:1024 sc0
	v_cvt_f32_u32_e32 v3, v2
	v_sub_u32_e32 v5, 0, v2
	v_rcp_iflag_f32_e32 v3, v3
	s_nop 0
	v_mul_f32_e32 v3, 0x4f7ffffe, v3
	v_cvt_u32_f32_e32 v3, v3
	v_mul_lo_u32 v5, v5, v3
	v_mul_hi_u32 v5, v3, v5
	v_add_u32_e32 v3, v3, v5
	s_waitcnt vmcnt(0) lgkmcnt(0)
	v_mul_hi_u32 v3, v4, v3
	v_mul_lo_u32 v5, v3, v2
	v_sub_u32_e32 v5, v4, v5
	v_cmp_ge_u32_e32 vcc, v5, v2
	v_add_u32_e32 v6, 1, v3
	s_nop 0
	v_cndmask_b32_e32 v3, v3, v6, vcc
	v_sub_u32_e32 v6, v5, v2
	v_cndmask_b32_e32 v5, v5, v6, vcc
	v_cmp_ge_u32_e32 vcc, v5, v2
	v_add_u32_e32 v5, 1, v3
	v_add_u32_e32 v6, 1, v4
	v_cndmask_b32_e32 v3, v3, v5, vcc
	v_mad_u64_u32 v[4:5], s[4:5], v2, v3, v[2:3]
	v_cmp_ne_u32_e32 vcc, v6, v4
	s_and_saveexec_b64 s[4:5], vcc
	s_xor_b64 s[24:25], exec, s[4:5]
	s_cbranch_execz .LBB0_835
	v_mad_u32_u24 v20, v3, v0, v0
	v_mov_b32_e32 v0, s2
	v_add_co_u32_e32 v4, vcc, 0x3000, v0
	v_mov_b32_e32 v0, s3
	s_nop 0
	v_addc_co_u32_e32 v5, vcc, 0, v0, vcc
	flat_load_dword v0, v[4:5] offset:1024 sc1
	s_add_u32 s30, s2, 0x3500
	s_addc_u32 s31, s3, 0
	s_waitcnt vmcnt(0) lgkmcnt(0)
	v_cmp_lt_u32_e32 vcc, v0, v20
	s_and_saveexec_b64 s[26:27], vcc
	s_cbranch_execz .LBB0_834
	s_mov_b32 s4, 1
	s_mov_b64 s[36:37], 0
	s_branch .LBB0_826

; __device__ __forceinline__ unsigned xb_ld(unsigned* p)              { return __hip_atomic_load(p, __ATOMIC_RELAXED, __HIP_MEMORY_SCOPE_AGENT); }
; #define XB_SPIN(cond, bar) do { unsigned _sp = 0; while (cond) { __builtin_amdgcn_s_sleep(1); \
;     if ((++_sp & 255u) == 0u) { if (xb_ld(&(bar)[XB_TMO])) break; if (_sp > XB_SPIN_CAP) { atomicAdd(&(bar)[XB_TMO], 1u); break; } } } } while (0)
; __device__ __forceinline__ void xcd_barrier(const XcdBarrier& b) {
;     ...
;             else XB_SPIN(xb_ld(&bar[XB_TOPGEN]) == tg, bar);
;             __builtin_amdgcn_fence(__ATOMIC_ACQUIRE, "agent");
;             asm volatile("s_waitcnt vmcnt(0)" ::: "memory");
;         } else {
;             XB_SPIN(xb_ld(&bar[XB_TOPGEN]) == gen, bar);
.LBB0_830:
	s_andn2_b64 s[10:11], s[40:41], exec
	s_and_b64 s[12:13], s[46:47], exec
	s_or_b64 s[40:41], s[10:11], s[12:13]
	s_and_saveexec_b64 s[46:47], s[44:45]
	s_cbranch_execz .LBB0_825
	v_mov_b64_e32 v[4:5], s[30:31]
	global_load_dword v0, v[4:5], off offset:-256 sc1
	s_add_i32 s4, s4, 1
	s_or_b64 s[40:41], s[40:41], exec
	s_waitcnt vmcnt(0) lgkmcnt(0)
	v_cmp_ge_u32_e32 vcc, v0, v20
	s_orn2_b64 s[42:43], vcc, exec
	s_branch .LBB0_825

; __device__ __forceinline__ unsigned xb_ld(unsigned* p)              { return __hip_atomic_load(p, __ATOMIC_RELAXED, __HIP_MEMORY_SCOPE_AGENT); }
; __device__ __forceinline__ unsigned xb_add(unsigned* p, unsigned v) { return __hip_atomic_fetch_add(p, v, __ATOMIC_RELAXED, __HIP_MEMORY_SCOPE_AGENT); }
; #define XB_SPIN(cond, bar) do { unsigned _sp = 0; while (cond) { __builtin_amdgcn_s_sleep(1); \
;     if ((++_sp & 255u) == 0u) { if (xb_ld(&(bar)[XB_TMO])) break; if (_sp > XB_SPIN_CAP) { atomicAdd(&(bar)[XB_TMO], 1u); break; } } } } while (0)
; __device__ __forceinline__ void xcd_barrier(const XcdBarrier& b) {
;     ...
;         const unsigned old = xb_add(&bar[XB_XSUB(b.x)], 1u);
;         const unsigned gen = old / nloc;
;         if (old + 1u == (gen + 1u) * nloc) {
;             __builtin_amdgcn_fence(__ATOMIC_RELEASE, "agent");
;             asm volatile("s_waitcnt vmcnt(0)" ::: "memory");
;             const unsigned og = xb_add(&bar[XB_TOP], 1u);
;             const unsigned tg = og / nx;
;             if (og + 1u == (tg + 1u) * nx) xb_add(&bar[XB_TOPGEN], 1u);
;             else XB_SPIN(xb_ld(&bar[XB_TOPGEN]) == tg, bar);
.LBB0_835:
	s_andn2_saveexec_b64 s[4:5], s[24:25]
	s_cbranch_execz .LBB0_851
	v_mov_b32_e32 v2, s2
	v_add_co_u32_e32 v2, vcc, 0x3000, v2
	v_mov_b32_e32 v3, s3
	buffer_wbl2 sc1
	s_waitcnt vmcnt(0)
	v_addc_co_u32_e32 v3, vcc, 0, v3, vcc
	flat_atomic_add v2, v[2:3], v210 offset:1024 sc0
	v_cvt_f32_u32_e32 v3, v0
	v_sub_u32_e32 v4, 0, v0
	s_add_u32 s24, s2, 0x3500
	s_addc_u32 s25, s3, 0
	v_rcp_iflag_f32_e32 v3, v3
	s_mov_b64 s[30:31], -1
	v_mul_f32_e32 v3, 0x4f7ffffe, v3
	v_cvt_u32_f32_e32 v3, v3
	v_mul_lo_u32 v4, v4, v3
	v_mul_hi_u32 v4, v3, v4
	v_add_u32_e32 v3, v3, v4
	s_waitcnt vmcnt(0) lgkmcnt(0)
	v_mul_hi_u32 v3, v2, v3
	v_mul_lo_u32 v4, v3, v0
	v_sub_u32_e32 v4, v2, v4
	v_cmp_ge_u32_e32 vcc, v4, v0
	v_add_u32_e32 v5, 1, v3
	s_nop 0
	v_cndmask_b32_e32 v3, v3, v5, vcc
	v_sub_u32_e32 v5, v4, v0
	v_cndmask_b32_e32 v4, v4, v5, vcc
	v_cmp_ge_u32_e32 vcc, v4, v0
	v_add_u32_e32 v4, 1, v3
	v_add_u32_e32 v5, 1, v2
	v_cndmask_b32_e32 v4, v3, v4, vcc
	v_mad_u64_u32 v[2:3], s[4:5], v0, v4, v[0:1]
	v_cmp_ne_u32_e32 vcc, v5, v2
	v_mov_b32_e32 v20, v2
	v_mov_b64_e32 v[2:3], s[24:25]
	s_and_saveexec_b64 s[26:27], vcc
	s_cbranch_execz .LBB0_848
	v_mov_b64_e32 v[2:3], s[24:25]
	global_load_dword v0, v[2:3], off offset:-256 sc1
	s_mov_b64 s[38:39], 0
	s_waitcnt vmcnt(0) lgkmcnt(0)
	v_cmp_lt_u32_e32 vcc, v0, v20
	s_and_saveexec_b64 s[36:37], vcc
	s_cbranch_execz .LBB0_847
	s_add_u32 s30, s2, 0x200
	s_addc_u32 s31, s3, 0
	s_mov_b32 s4, 1
	s_mov_b64 s[2:3], 0
	s_branch .LBB0_840

; __device__ __forceinline__ unsigned xb_ld(unsigned* p)              { return __hip_atomic_load(p, __ATOMIC_RELAXED, __HIP_MEMORY_SCOPE_AGENT); }
; #define XB_SPIN(cond, bar) do { unsigned _sp = 0; while (cond) { __builtin_amdgcn_s_sleep(1); \
;     if ((++_sp & 255u) == 0u) { if (xb_ld(&(bar)[XB_TMO])) break; if (_sp > XB_SPIN_CAP) { atomicAdd(&(bar)[XB_TMO], 1u); break; } } } } while (0)
; __device__ __forceinline__ void xcd_barrier(const XcdBarrier& b) {
;     ...
;             else XB_SPIN(xb_ld(&bar[XB_TOPGEN]) == tg, bar);
.LBB0_845:
	v_mov_b64_e32 v[2:3], s[24:25]
	global_load_dword v0, v[2:3], off offset:-256 sc1
	s_add_i32 s4, s4, 1
	s_or_b64 s[42:43], s[42:43], exec
	s_waitcnt vmcnt(0) lgkmcnt(0)
	v_cmp_ge_u32_e32 vcc, v0, v20
	s_orn2_b64 s[40:41], vcc, exec
	s_branch .LBB0_839
